# GEMM K-loops SP1 segments: all 16 ds_reads issued before the 4 LDS-DMA pieces; on top of v015
# speedup vs baseline: 1.0047x; 1.0018x over previous
; #define PG8_STAGE(bufoff, gbase, voff) do { _Pragma("unroll") for (int _i = 0; _i < 2; ++_i) \
;         __builtin_amdgcn_global_load_lds((const unsigned*)((const char*)(gbase) + (voff)[_i]), (LAS unsigned*)(lds + (bufoff) + ldsw + _i * 8192), 16, 0, 0); } while (0)
; #define PG8_LDA(dst, b, h) do { _Pragma("unroll") for (int m = 0; m < 4; ++m) _Pragma("unroll") for (int k = 0; k < 2; ++k) dst[m][k] = *(const LAS bf16x8*)(lds + PG8_SA(b, h) + aoff + m * 2048 + k * 1024); } while (0)
; #define PG8_LDB(dst, b, h) do { _Pragma("unroll") for (int n = 0; n < 2; ++n) _Pragma("unroll") for (int k = 0; k < 2; ++k) dst[n][k] = *(const LAS bf16x8*)(lds + PG8_SB(b, h) + boff + n * 2048 + k * 1024); } while (0)
; #define PG8_WAIT_V(n) asm volatile("s_waitcnt vmcnt(" #n ")" ::: "memory")
; #define PG8_WAIT_L(n) asm volatile("s_waitcnt lgkmcnt(" #n ")" ::: "memory")
; #define PG8_BAR __builtin_amdgcn_s_barrier()
; #define PG8_SCHED __builtin_amdgcn_sched_barrier(0)
; template <class Epi, class Sched, bool I8 = false>
; __device__ __forceinline__ void gemm_phase(LAS unsigned char* lds, const Gemm g, const Sched& S, const Epi& E) {
;     ...
;             PG8_LDB(B0, 0, 0); PG8_LDB(B1, 0, 1); PG8_SCHED; PG8_LDA(At, 0, 0); PG8_STAGE(PG8_SA(1, 1), a1 + hstepA, voffA);
;             PG8_WAIT_V(8); PG8_WAIT_L(0); PG8_BAR; PG8_MMA(0, 0, At, B0); PG8_MMA(0, 1, At, B1); PG8_BAR; PG8_SCHED;
;             PG8_LDA(At, 0, 1); PG8_STAGE(PG8_SB(0, 0), b2, voffB); PG8_STAGE(PG8_SB(0, 1), b2 + hstepB, voffB); PG8_STAGE(PG8_SA(0, 0), a2, voffA);
;             PG8_WAIT_V(8); PG8_WAIT_L(0); PG8_BAR; PG8_MMA(1, 0, At, B0); PG8_MMA(1, 1, At, B1); PG8_BAR; PG8_SCHED;
.LBB0_1169:
	ds_read_b128 v[90:93], v169
	ds_read_b128 v[98:101], v169 offset:1024
	ds_read_b128 v[172:175], v169 offset:2048
	ds_read_b128 v[176:179], v169 offset:3072
	ds_read_b128 v[180:183], v170
	ds_read_b128 v[184:187], v170 offset:1024
	ds_read_b128 v[188:191], v170 offset:2048
	ds_read_b128 v[192:195], v170 offset:3072
	s_add_u32 s22, s20, 0x4000
	s_addc_u32 s23, s21, 0
	s_cmp_eq_u32 s53, 28
	s_cselect_b32 s26, s49, s22
	s_cselect_b32 s27, s13, s23
	s_cselect_b32 s24, s50, s51
	s_cselect_b32 s25, s11, s52
	s_add_u32 s22, s26, 0x8000
	s_addc_u32 s23, s27, 0
	s_sub_u32 s98, s20, 0x4000
	s_subb_u32 s99, s21, 0
	ds_read_b128 v[196:199], v171
	ds_read_b128 v[200:203], v171 offset:1024
	ds_read_b128 v[204:207], v171 offset:2048
	ds_read_b128 v[208:211], v171 offset:3072
	ds_read_b128 v[212:215], v171 offset:4096
	ds_read_b128 v[216:219], v171 offset:5120
	ds_read_b128 v[220:223], v171 offset:6144
	ds_read_b128 v[224:227], v171 offset:7168
	s_mov_b32 m0, s43
	s_nop 0
	global_load_lds_dwordx4 v144, s[98:99]
	s_mov_b32 m0, s44
	s_nop 0
	global_load_lds_dwordx4 v140, s[98:99]
	s_add_i32 m0, s36, 0xc000
	s_nop 0
	global_load_lds_dwordx4 v148, s[20:21]
	s_add_i32 m0, s36, 0xe000
	s_nop 0
	global_load_lds_dwordx4 v150, s[20:21]
	s_waitcnt vmcnt(8)
	s_waitcnt lgkmcnt(0)
	s_barrier
	s_waitcnt lgkmcnt(0)
	v_mfma_i32_16x16x64_i8 v[134:137], v[90:93], v[196:199], v[134:137]
	v_mfma_i32_16x16x64_i8 v[130:133], v[172:175], v[196:199], v[130:133]
	v_mfma_i32_16x16x64_i8 v[118:121], v[90:93], v[204:207], v[118:121]
	v_mfma_i32_16x16x64_i8 v[114:117], v[172:175], v[204:207], v[114:117]
	v_mfma_i32_16x16x64_i8 v[102:105], v[90:93], v[212:215], v[102:105]
	v_mfma_i32_16x16x64_i8 v[94:97], v[172:175], v[212:215], v[94:97]
	v_mfma_i32_16x16x64_i8 v[78:81], v[90:93], v[220:223], v[78:81]
	v_mfma_i32_16x16x64_i8 v[74:77], v[172:175], v[220:223], v[74:77]
	v_mfma_i32_16x16x64_i8 v[134:137], v[98:101], v[200:203], v[134:137]
	v_mfma_i32_16x16x64_i8 v[130:133], v[176:179], v[200:203], v[130:133]
	v_mfma_i32_16x16x64_i8 v[118:121], v[98:101], v[208:211], v[118:121]
	v_mfma_i32_16x16x64_i8 v[114:117], v[176:179], v[208:211], v[114:117]
	v_mfma_i32_16x16x64_i8 v[102:105], v[98:101], v[216:219], v[102:105]
	v_mfma_i32_16x16x64_i8 v[94:97], v[176:179], v[216:219], v[94:97]
	v_mfma_i32_16x16x64_i8 v[78:81], v[98:101], v[224:227], v[78:81]
	v_mfma_i32_16x16x64_i8 v[74:77], v[176:179], v[224:227], v[74:77]
	v_mfma_i32_16x16x64_i8 v[126:129], v[180:183], v[196:199], v[126:129]
	v_mfma_i32_16x16x64_i8 v[122:125], v[188:191], v[196:199], v[122:125]
	v_mfma_i32_16x16x64_i8 v[110:113], v[180:183], v[204:207], v[110:113]
	v_mfma_i32_16x16x64_i8 v[106:109], v[188:191], v[204:207], v[106:109]
	v_mfma_i32_16x16x64_i8 v[86:89], v[180:183], v[212:215], v[86:89]
	v_mfma_i32_16x16x64_i8 v[82:85], v[188:191], v[212:215], v[82:85]
	v_mfma_i32_16x16x64_i8 v[70:73], v[180:183], v[220:223], v[70:73]
	v_mfma_i32_16x16x64_i8 v[66:69], v[188:191], v[220:223], v[66:69]
	v_mfma_i32_16x16x64_i8 v[126:129], v[184:187], v[200:203], v[126:129]
	v_mfma_i32_16x16x64_i8 v[122:125], v[192:195], v[200:203], v[122:125]
	v_mfma_i32_16x16x64_i8 v[110:113], v[184:187], v[208:211], v[110:113]
	v_mfma_i32_16x16x64_i8 v[106:109], v[192:195], v[208:211], v[106:109]
	v_mfma_i32_16x16x64_i8 v[86:89], v[184:187], v[216:219], v[86:89]
	v_mfma_i32_16x16x64_i8 v[82:85], v[192:195], v[216:219], v[82:85]
	v_mfma_i32_16x16x64_i8 v[70:73], v[184:187], v[224:227], v[70:73]
	v_mfma_i32_16x16x64_i8 v[66:69], v[192:195], v[224:227], v[66:69]
	s_barrier
	s_add_i32 s54, s46, s33
	s_mov_b32 m0, s54
	ds_read_b128 v[196:199], v171 offset:16384
	ds_read_b128 v[200:203], v171 offset:17408
	ds_read_b128 v[204:207], v171 offset:18432
	ds_read_b128 v[208:211], v171 offset:19456
	ds_read_b128 v[212:215], v171 offset:20480
	ds_read_b128 v[216:219], v171 offset:21504
	ds_read_b128 v[220:223], v171 offset:22528
	ds_read_b128 v[224:227], v171 offset:23552
	global_load_lds_dwordx4 v142, s[24:25]
	s_add_i32 m0, s54, 0x2000
	s_add_u32 s54, s24, 0x4000
	s_addc_u32 s55, s25, 0
	s_add_i32 s56, s47, s33
	global_load_lds_dwordx4 v138, s[24:25]
	s_mov_b32 m0, s56
	s_nop 0
	global_load_lds_dwordx4 v142, s[54:55]
	s_add_i32 m0, s56, 0x2000
	s_nop 0
	global_load_lds_dwordx4 v138, s[54:55]
	s_waitcnt vmcnt(6)
	s_waitcnt lgkmcnt(0)
	s_barrier
	s_waitcnt lgkmcnt(0)
	v_mfma_i32_16x16x64_i8 v[62:65], v[90:93], v[196:199], v[62:65]
	v_mfma_i32_16x16x64_i8 v[58:61], v[172:175], v[196:199], v[58:61]
	v_mfma_i32_16x16x64_i8 v[46:49], v[90:93], v[204:207], v[46:49]
	v_mfma_i32_16x16x64_i8 v[42:45], v[172:175], v[204:207], v[42:45]
	v_mfma_i32_16x16x64_i8 v[30:33], v[90:93], v[212:215], v[30:33]
	v_mfma_i32_16x16x64_i8 v[26:29], v[172:175], v[212:215], v[26:29]
	v_mfma_i32_16x16x64_i8 v[14:17], v[90:93], v[220:223], v[14:17]
	v_mfma_i32_16x16x64_i8 v[10:13], v[172:175], v[220:223], v[10:13]
	v_mfma_i32_16x16x64_i8 v[62:65], v[98:101], v[200:203], v[62:65]
	v_mfma_i32_16x16x64_i8 v[58:61], v[176:179], v[200:203], v[58:61]
	v_mfma_i32_16x16x64_i8 v[46:49], v[98:101], v[208:211], v[46:49]
	v_mfma_i32_16x16x64_i8 v[42:45], v[176:179], v[208:211], v[42:45]
	v_mfma_i32_16x16x64_i8 v[30:33], v[98:101], v[216:219], v[30:33]
	v_mfma_i32_16x16x64_i8 v[26:29], v[176:179], v[216:219], v[26:29]
	v_mfma_i32_16x16x64_i8 v[14:17], v[98:101], v[224:227], v[14:17]
	v_mfma_i32_16x16x64_i8 v[10:13], v[176:179], v[224:227], v[10:13]
	v_mfma_i32_16x16x64_i8 v[54:57], v[180:183], v[196:199], v[54:57]
	v_mfma_i32_16x16x64_i8 v[50:53], v[188:191], v[196:199], v[50:53]
	v_mfma_i32_16x16x64_i8 v[38:41], v[180:183], v[204:207], v[38:41]
	v_mfma_i32_16x16x64_i8 v[34:37], v[188:191], v[204:207], v[34:37]
	v_mfma_i32_16x16x64_i8 v[22:25], v[180:183], v[212:215], v[22:25]
	v_mfma_i32_16x16x64_i8 v[18:21], v[188:191], v[212:215], v[18:21]
	v_mfma_i32_16x16x64_i8 v[6:9], v[180:183], v[220:223], v[6:9]
	v_mfma_i32_16x16x64_i8 v[2:5], v[188:191], v[220:223], v[2:5]
	v_mfma_i32_16x16x64_i8 v[54:57], v[184:187], v[200:203], v[54:57]
	v_mfma_i32_16x16x64_i8 v[50:53], v[192:195], v[200:203], v[50:53]
	v_mfma_i32_16x16x64_i8 v[38:41], v[184:187], v[208:211], v[38:41]
	v_mfma_i32_16x16x64_i8 v[34:37], v[192:195], v[208:211], v[34:37]
	v_mfma_i32_16x16x64_i8 v[22:25], v[184:187], v[216:219], v[22:25]
	v_mfma_i32_16x16x64_i8 v[18:21], v[192:195], v[216:219], v[18:21]
	v_mfma_i32_16x16x64_i8 v[6:9], v[184:187], v[224:227], v[6:9]
	v_mfma_i32_16x16x64_i8 v[2:5], v[192:195], v[224:227], v[2:5]
	s_barrier
; #define PG8_STAGE(bufoff, gbase, voff) do { _Pragma("unroll") for (int _i = 0; _i < 2; ++_i) \
;         __builtin_amdgcn_global_load_lds((const unsigned*)((const char*)(gbase) + (voff)[_i]), (LAS unsigned*)(lds + (bufoff) + ldsw + _i * 8192), 16, 0, 0); } while (0)
; #define PG8_LDA(dst, b, h) do { _Pragma("unroll") for (int m = 0; m < 4; ++m) _Pragma("unroll") for (int k = 0; k < 2; ++k) dst[m][k] = *(const LAS bf16x8*)(lds + PG8_SA(b, h) + aoff + m * 2048 + k * 1024); } while (0)
; #define PG8_LDB(dst, b, h) do { _Pragma("unroll") for (int n = 0; n < 2; ++n) _Pragma("unroll") for (int k = 0; k < 2; ++k) dst[n][k] = *(const LAS bf16x8*)(lds + PG8_SB(b, h) + boff + n * 2048 + k * 1024); } while (0)
; #define PG8_WAIT_V(n) asm volatile("s_waitcnt vmcnt(" #n ")" ::: "memory")
; #define PG8_WAIT_L(n) asm volatile("s_waitcnt lgkmcnt(" #n ")" ::: "memory")
; #define PG8_BAR __builtin_amdgcn_s_barrier()
; #define PG8_SCHED __builtin_amdgcn_sched_barrier(0)
; template <class Epi, class Sched, bool I8 = false>
; __device__ __forceinline__ void gemm_phase(LAS unsigned char* lds, const Gemm g, const Sched& S, const Epi& E) {
;     ...
;             PG8_LDB(B0, 1, 0); PG8_LDB(B1, 1, 1); PG8_SCHED; PG8_LDA(At, 1, 0); PG8_STAGE(PG8_SA(0, 1), a2 + hstepA, voffA);
;             PG8_WAIT_V(8); PG8_WAIT_L(0); PG8_BAR; PG8_MMA(0, 0, At, B0); PG8_MMA(0, 1, At, B1); PG8_BAR; PG8_SCHED;
;             PG8_LDA(At, 1, 1); PG8_STAGE(PG8_SB(1, 0), b3, voffB); PG8_STAGE(PG8_SB(1, 1), b3 + hstepB, voffB); PG8_STAGE(PG8_SA(1, 0), a3, voffA);
;             PG8_WAIT_V(8); PG8_WAIT_L(0); PG8_BAR; PG8_MMA(1, 0, At, B0); PG8_MMA(1, 1, At, B1); PG8_BAR; PG8_SCHED;
;         }
	s_add_i32 s54, 0, 0x18000
	v_add_u32_e32 v146, s54, v165
	s_add_i32 s55, 0, 0x1c000
	ds_read_b128 v[90:93], v146
	ds_read_b128 v[98:101], v146 offset:1024
	ds_read_b128 v[172:175], v146 offset:2048
	ds_read_b128 v[176:179], v146 offset:3072
	v_add_u32_e32 v146, s55, v165
	ds_read_b128 v[180:183], v146
	ds_read_b128 v[184:187], v146 offset:1024
	ds_read_b128 v[188:191], v146 offset:2048
	ds_read_b128 v[192:195], v146 offset:3072
	ds_read_b128 v[196:199], v171 offset:32768
	ds_read_b128 v[200:203], v171 offset:33792
	ds_read_b128 v[204:207], v171 offset:34816
	ds_read_b128 v[208:211], v171 offset:35840
	ds_read_b128 v[212:215], v171 offset:36864
	ds_read_b128 v[216:219], v171 offset:37888
	ds_read_b128 v[220:223], v171 offset:38912
	ds_read_b128 v[224:227], v171 offset:39936
	s_mov_b32 m0, s36
	s_nop 0
	global_load_lds_dwordx4 v144, s[26:27]
	s_mov_b32 m0, s37
	s_nop 0
	global_load_lds_dwordx4 v140, s[26:27]
	s_add_u32 s26, s26, 0x4000
	s_addc_u32 s27, s27, 0
	s_mov_b32 m0, s38
	s_nop 0
	global_load_lds_dwordx4 v144, s[26:27]
	s_mov_b32 m0, s39
	s_nop 0
	global_load_lds_dwordx4 v140, s[26:27]
	s_waitcnt vmcnt(8)
	s_waitcnt lgkmcnt(0)
	s_barrier
	s_waitcnt lgkmcnt(0)
	v_mfma_i32_16x16x64_i8 v[134:137], v[90:93], v[196:199], v[134:137]
	v_mfma_i32_16x16x64_i8 v[130:133], v[172:175], v[196:199], v[130:133]
	v_mfma_i32_16x16x64_i8 v[118:121], v[90:93], v[204:207], v[118:121]
	v_mfma_i32_16x16x64_i8 v[114:117], v[172:175], v[204:207], v[114:117]
	v_mfma_i32_16x16x64_i8 v[102:105], v[90:93], v[212:215], v[102:105]
	v_mfma_i32_16x16x64_i8 v[94:97], v[172:175], v[212:215], v[94:97]
	v_mfma_i32_16x16x64_i8 v[78:81], v[90:93], v[220:223], v[78:81]
	v_mfma_i32_16x16x64_i8 v[74:77], v[172:175], v[220:223], v[74:77]
	v_mfma_i32_16x16x64_i8 v[134:137], v[98:101], v[200:203], v[134:137]
	v_mfma_i32_16x16x64_i8 v[130:133], v[176:179], v[200:203], v[130:133]
	v_mfma_i32_16x16x64_i8 v[118:121], v[98:101], v[208:211], v[118:121]
	v_mfma_i32_16x16x64_i8 v[114:117], v[176:179], v[208:211], v[114:117]
	v_mfma_i32_16x16x64_i8 v[102:105], v[98:101], v[216:219], v[102:105]
	v_mfma_i32_16x16x64_i8 v[94:97], v[176:179], v[216:219], v[94:97]
	v_mfma_i32_16x16x64_i8 v[78:81], v[98:101], v[224:227], v[78:81]
	v_mfma_i32_16x16x64_i8 v[74:77], v[176:179], v[224:227], v[74:77]
	v_mfma_i32_16x16x64_i8 v[126:129], v[180:183], v[196:199], v[126:129]
	v_mfma_i32_16x16x64_i8 v[122:125], v[188:191], v[196:199], v[122:125]
	v_mfma_i32_16x16x64_i8 v[110:113], v[180:183], v[204:207], v[110:113]
	v_mfma_i32_16x16x64_i8 v[106:109], v[188:191], v[204:207], v[106:109]
	v_mfma_i32_16x16x64_i8 v[86:89], v[180:183], v[212:215], v[86:89]
	v_mfma_i32_16x16x64_i8 v[82:85], v[188:191], v[212:215], v[82:85]
	v_mfma_i32_16x16x64_i8 v[70:73], v[180:183], v[220:223], v[70:73]
	v_mfma_i32_16x16x64_i8 v[66:69], v[188:191], v[220:223], v[66:69]
	v_mfma_i32_16x16x64_i8 v[126:129], v[184:187], v[200:203], v[126:129]
	v_mfma_i32_16x16x64_i8 v[122:125], v[192:195], v[200:203], v[122:125]
	v_mfma_i32_16x16x64_i8 v[110:113], v[184:187], v[208:211], v[110:113]
	v_mfma_i32_16x16x64_i8 v[106:109], v[192:195], v[208:211], v[106:109]
	v_mfma_i32_16x16x64_i8 v[86:89], v[184:187], v[216:219], v[86:89]
	v_mfma_i32_16x16x64_i8 v[82:85], v[192:195], v[216:219], v[82:85]
	v_mfma_i32_16x16x64_i8 v[70:73], v[184:187], v[224:227], v[70:73]
	v_mfma_i32_16x16x64_i8 v[66:69], v[192:195], v[224:227], v[66:69]
	s_barrier
	s_add_u32 s26, s24, 0x8000
	s_addc_u32 s27, s25, 0
	s_add_i32 s54, s54, s33
	s_mov_b32 m0, s54
	ds_read_b128 v[196:199], v171 offset:49152
	ds_read_b128 v[200:203], v171 offset:50176
	ds_read_b128 v[204:207], v171 offset:51200
	ds_read_b128 v[208:211], v171 offset:52224
	ds_read_b128 v[212:215], v171 offset:53248
	ds_read_b128 v[216:219], v171 offset:54272
	ds_read_b128 v[220:223], v171 offset:55296
	ds_read_b128 v[224:227], v171 offset:56320
	global_load_lds_dwordx4 v142, s[26:27]
	s_add_i32 m0, s54, 0x2000
	s_add_u32 s24, s24, 0xc000
	v_lshl_add_u64 v[158:159], s[26:27], 0, v[138:139]
	s_addc_u32 s25, s25, 0
	s_add_i32 s26, s55, s33
	global_load_lds_dwordx4 v[158:159], off
	s_mov_b32 m0, s26
	s_nop 0
	global_load_lds_dwordx4 v142, s[24:25]
	s_add_i32 m0, s26, 0x2000
	s_nop 0
	global_load_lds_dwordx4 v138, s[24:25]
	s_waitcnt vmcnt(6)
	s_waitcnt lgkmcnt(0)
	s_barrier
	s_waitcnt lgkmcnt(0)
	v_mfma_i32_16x16x64_i8 v[62:65], v[90:93], v[196:199], v[62:65]
	v_mfma_i32_16x16x64_i8 v[58:61], v[172:175], v[196:199], v[58:61]
	v_mfma_i32_16x16x64_i8 v[46:49], v[90:93], v[204:207], v[46:49]
	v_mfma_i32_16x16x64_i8 v[42:45], v[172:175], v[204:207], v[42:45]
	v_mfma_i32_16x16x64_i8 v[30:33], v[90:93], v[212:215], v[30:33]
	v_mfma_i32_16x16x64_i8 v[26:29], v[172:175], v[212:215], v[26:29]
	v_mfma_i32_16x16x64_i8 v[14:17], v[90:93], v[220:223], v[14:17]
	v_mfma_i32_16x16x64_i8 v[10:13], v[172:175], v[220:223], v[10:13]
	v_mfma_i32_16x16x64_i8 v[62:65], v[98:101], v[200:203], v[62:65]
	v_mfma_i32_16x16x64_i8 v[58:61], v[176:179], v[200:203], v[58:61]
	v_mfma_i32_16x16x64_i8 v[46:49], v[98:101], v[208:211], v[46:49]
	v_mfma_i32_16x16x64_i8 v[42:45], v[176:179], v[208:211], v[42:45]
	v_mfma_i32_16x16x64_i8 v[30:33], v[98:101], v[216:219], v[30:33]
	v_mfma_i32_16x16x64_i8 v[26:29], v[176:179], v[216:219], v[26:29]
	v_mfma_i32_16x16x64_i8 v[14:17], v[98:101], v[224:227], v[14:17]
	v_mfma_i32_16x16x64_i8 v[10:13], v[176:179], v[224:227], v[10:13]
	v_mfma_i32_16x16x64_i8 v[54:57], v[180:183], v[196:199], v[54:57]
	v_mfma_i32_16x16x64_i8 v[50:53], v[188:191], v[196:199], v[50:53]
	v_mfma_i32_16x16x64_i8 v[38:41], v[180:183], v[204:207], v[38:41]
	v_mfma_i32_16x16x64_i8 v[34:37], v[188:191], v[204:207], v[34:37]
	v_mfma_i32_16x16x64_i8 v[22:25], v[180:183], v[212:215], v[22:25]
	v_mfma_i32_16x16x64_i8 v[18:21], v[188:191], v[212:215], v[18:21]
	v_mfma_i32_16x16x64_i8 v[6:9], v[180:183], v[220:223], v[6:9]
	v_mfma_i32_16x16x64_i8 v[2:5], v[188:191], v[220:223], v[2:5]
	v_mfma_i32_16x16x64_i8 v[54:57], v[184:187], v[200:203], v[54:57]
	v_mfma_i32_16x16x64_i8 v[50:53], v[192:195], v[200:203], v[50:53]
	v_mfma_i32_16x16x64_i8 v[38:41], v[184:187], v[208:211], v[38:41]
	v_mfma_i32_16x16x64_i8 v[34:37], v[192:195], v[208:211], v[34:37]
	v_mfma_i32_16x16x64_i8 v[22:25], v[184:187], v[216:219], v[22:25]
	v_mfma_i32_16x16x64_i8 v[18:21], v[192:195], v[216:219], v[18:21]
	v_mfma_i32_16x16x64_i8 v[6:9], v[184:187], v[224:227], v[6:9]
	v_mfma_i32_16x16x64_i8 v[2:5], v[192:195], v[224:227], v[2:5]
	s_barrier
	s_add_i32 s53, s53, 2
	s_add_u32 s20, s20, 0x10000
	s_addc_u32 s21, s21, 0
	s_add_u32 s51, s51, 0x10000
	s_addc_u32 s52, s52, 0
	s_cmp_gt_u32 s53, 29
	s_cbranch_scc0 .LBB0_1169
	s_and_b64 vcc, exec, s[8:9]
	s_cbranch_vccz .LBB0_1172
	s_barrier

; #define PG8_STAGE(bufoff, gbase, voff) do { _Pragma("unroll") for (int _i = 0; _i < 2; ++_i) \
;         __builtin_amdgcn_global_load_lds((const unsigned*)((const char*)(gbase) + (voff)[_i]), (LAS unsigned*)(lds + (bufoff) + ldsw + _i * 8192), 16, 0, 0); } while (0)
; #define PG8_LDA(dst, b, h) do { _Pragma("unroll") for (int m = 0; m < 4; ++m) _Pragma("unroll") for (int k = 0; k < 2; ++k) dst[m][k] = *(const LAS bf16x8*)(lds + PG8_SA(b, h) + aoff + m * 2048 + k * 1024); } while (0)
; #define PG8_LDB(dst, b, h) do { _Pragma("unroll") for (int n = 0; n < 2; ++n) _Pragma("unroll") for (int k = 0; k < 2; ++k) dst[n][k] = *(const LAS bf16x8*)(lds + PG8_SB(b, h) + boff + n * 2048 + k * 1024); } while (0)
; #define PG8_WAIT_V(n) asm volatile("s_waitcnt vmcnt(" #n ")" ::: "memory")
; #define PG8_WAIT_L(n) asm volatile("s_waitcnt lgkmcnt(" #n ")" ::: "memory")
; #define PG8_BAR __builtin_amdgcn_s_barrier()
; #define PG8_SCHED __builtin_amdgcn_sched_barrier(0)
; template <class Epi, class Sched, bool I8 = false>
; __device__ __forceinline__ void gemm_phase(LAS unsigned char* lds, const Gemm g, const Sched& S, const Epi& E) {
;     ...
;             PG8_LDB(B0, 0, 0); PG8_LDB(B1, 0, 1); PG8_SCHED; PG8_LDA(At, 0, 0); PG8_STAGE(PG8_SA(1, 1), a1 + hstepA, voffA);
;             PG8_WAIT_V(8); PG8_WAIT_L(0); PG8_BAR; PG8_MMA(0, 0, At, B0); PG8_MMA(0, 1, At, B1); PG8_BAR; PG8_SCHED;
;             PG8_LDA(At, 0, 1); PG8_STAGE(PG8_SB(0, 0), b2, voffB); PG8_STAGE(PG8_SB(0, 1), b2 + hstepB, voffB); PG8_STAGE(PG8_SA(0, 0), a2, voffA);
;             PG8_WAIT_V(8); PG8_WAIT_L(0); PG8_BAR; PG8_MMA(1, 0, At, B0); PG8_MMA(1, 1, At, B1); PG8_BAR; PG8_SCHED;
.LBB0_1393:
	ds_read_b128 v[66:69], v180
	ds_read_b128 v[70:73], v180 offset:1024
	ds_read_b128 v[74:77], v180 offset:2048
	ds_read_b128 v[78:81], v180 offset:3072
	ds_read_b128 v[146:149], v181
	ds_read_b128 v[150:153], v181 offset:1024
	ds_read_b128 v[174:177], v181 offset:2048
	ds_read_b128 v[184:187], v181 offset:3072
	s_add_u32 s20, s18, 0x4000
	s_addc_u32 s21, s19, 0
	s_cmpk_eq_i32 s49, 0x52
	s_cselect_b32 s24, s0, s20
	s_cselect_b32 s25, s1, s21
	s_cselect_b32 s22, s16, s47
	s_cselect_b32 s23, s17, s48
	s_add_u32 s20, s24, 0x8000
	s_addc_u32 s21, s25, 0
	s_sub_u32 s98, s18, 0x4000
	s_subb_u32 s99, s19, 0
	ds_read_b128 v[188:191], v182
	ds_read_b128 v[192:195], v182 offset:1024
	ds_read_b128 v[196:199], v182 offset:2048
	ds_read_b128 v[200:203], v182 offset:3072
	ds_read_b128 v[204:207], v182 offset:4096
	ds_read_b128 v[208:211], v182 offset:5120
	ds_read_b128 v[212:215], v182 offset:6144
	ds_read_b128 v[216:219], v182 offset:7168
	s_mov_b32 m0, s37
	s_nop 0
	global_load_lds_dwordx4 v156, s[98:99]
	s_mov_b32 m0, s38
	s_nop 0
	global_load_lds_dwordx4 v160, s[98:99]
	s_add_i32 m0, s31, 0xc000
	s_nop 0
	global_load_lds_dwordx4 v166, s[18:19]
	s_add_i32 m0, s31, 0xe000
	s_nop 0
	global_load_lds_dwordx4 v168, s[18:19]
	s_waitcnt vmcnt(8)
	s_waitcnt lgkmcnt(0)
	s_barrier
	s_waitcnt lgkmcnt(0)
	v_mfma_i32_16x16x64_i8 v[142:145], v[66:69], v[188:191], v[142:145]
	v_mfma_i32_16x16x64_i8 v[138:141], v[74:77], v[188:191], v[138:141]
	v_mfma_i32_16x16x64_i8 v[126:129], v[66:69], v[196:199], v[126:129]
	v_mfma_i32_16x16x64_i8 v[122:125], v[74:77], v[196:199], v[122:125]
	v_mfma_i32_16x16x64_i8 v[110:113], v[66:69], v[204:207], v[110:113]
	v_mfma_i32_16x16x64_i8 v[106:109], v[74:77], v[204:207], v[106:109]
	v_mfma_i32_16x16x64_i8 v[94:97], v[66:69], v[212:215], v[94:97]
	v_mfma_i32_16x16x64_i8 v[90:93], v[74:77], v[212:215], v[90:93]
	v_mfma_i32_16x16x64_i8 v[142:145], v[70:73], v[192:195], v[142:145]
	v_mfma_i32_16x16x64_i8 v[138:141], v[78:81], v[192:195], v[138:141]
	v_mfma_i32_16x16x64_i8 v[126:129], v[70:73], v[200:203], v[126:129]
	v_mfma_i32_16x16x64_i8 v[122:125], v[78:81], v[200:203], v[122:125]
	v_mfma_i32_16x16x64_i8 v[110:113], v[70:73], v[208:211], v[110:113]
	v_mfma_i32_16x16x64_i8 v[106:109], v[78:81], v[208:211], v[106:109]
	v_mfma_i32_16x16x64_i8 v[94:97], v[70:73], v[216:219], v[94:97]
	v_mfma_i32_16x16x64_i8 v[90:93], v[78:81], v[216:219], v[90:93]
	v_mfma_i32_16x16x64_i8 v[134:137], v[146:149], v[188:191], v[134:137]
	v_mfma_i32_16x16x64_i8 v[130:133], v[174:177], v[188:191], v[130:133]
	v_mfma_i32_16x16x64_i8 v[118:121], v[146:149], v[196:199], v[118:121]
	v_mfma_i32_16x16x64_i8 v[114:117], v[174:177], v[196:199], v[114:117]
	v_mfma_i32_16x16x64_i8 v[102:105], v[146:149], v[204:207], v[102:105]
	v_mfma_i32_16x16x64_i8 v[98:101], v[174:177], v[204:207], v[98:101]
	v_mfma_i32_16x16x64_i8 v[86:89], v[146:149], v[212:215], v[86:89]
	v_mfma_i32_16x16x64_i8 v[82:85], v[174:177], v[212:215], v[82:85]
	v_mfma_i32_16x16x64_i8 v[134:137], v[150:153], v[192:195], v[134:137]
	v_mfma_i32_16x16x64_i8 v[130:133], v[184:187], v[192:195], v[130:133]
	v_mfma_i32_16x16x64_i8 v[118:121], v[150:153], v[200:203], v[118:121]
	v_mfma_i32_16x16x64_i8 v[114:117], v[184:187], v[200:203], v[114:117]
	v_mfma_i32_16x16x64_i8 v[102:105], v[150:153], v[208:211], v[102:105]
	v_mfma_i32_16x16x64_i8 v[98:101], v[184:187], v[208:211], v[98:101]
	v_mfma_i32_16x16x64_i8 v[86:89], v[150:153], v[216:219], v[86:89]
	v_mfma_i32_16x16x64_i8 v[82:85], v[184:187], v[216:219], v[82:85]
	s_barrier
	s_add_i32 s50, s41, s30
	s_mov_b32 m0, s50
	ds_read_b128 v[188:191], v182 offset:16384
	ds_read_b128 v[192:195], v182 offset:17408
	ds_read_b128 v[196:199], v182 offset:18432
	ds_read_b128 v[200:203], v182 offset:19456
	ds_read_b128 v[204:207], v182 offset:20480
	ds_read_b128 v[208:211], v182 offset:21504
	ds_read_b128 v[212:215], v182 offset:22528
	ds_read_b128 v[216:219], v182 offset:23552
	global_load_lds_dwordx4 v158, s[22:23]
	s_add_i32 m0, s50, 0x2000
	s_add_u32 s50, s22, 0x4000
	s_addc_u32 s51, s23, 0
	s_add_i32 s52, s42, s30
	global_load_lds_dwordx4 v162, s[22:23]
	s_mov_b32 m0, s52
	s_nop 0
	global_load_lds_dwordx4 v158, s[50:51]
	s_add_i32 m0, s52, 0x2000
	s_nop 0
	global_load_lds_dwordx4 v162, s[50:51]
	s_waitcnt vmcnt(6)
	s_waitcnt lgkmcnt(0)
	s_barrier
	s_waitcnt lgkmcnt(0)
	v_mfma_i32_16x16x64_i8 v[62:65], v[66:69], v[188:191], v[62:65]
	v_mfma_i32_16x16x64_i8 v[58:61], v[74:77], v[188:191], v[58:61]
	v_mfma_i32_16x16x64_i8 v[46:49], v[66:69], v[196:199], v[46:49]
	v_mfma_i32_16x16x64_i8 v[42:45], v[74:77], v[196:199], v[42:45]
	v_mfma_i32_16x16x64_i8 v[30:33], v[66:69], v[204:207], v[30:33]
	v_mfma_i32_16x16x64_i8 v[26:29], v[74:77], v[204:207], v[26:29]
	v_mfma_i32_16x16x64_i8 v[14:17], v[66:69], v[212:215], v[14:17]
	v_mfma_i32_16x16x64_i8 v[10:13], v[74:77], v[212:215], v[10:13]
	v_mfma_i32_16x16x64_i8 v[62:65], v[70:73], v[192:195], v[62:65]
	v_mfma_i32_16x16x64_i8 v[58:61], v[78:81], v[192:195], v[58:61]
	v_mfma_i32_16x16x64_i8 v[46:49], v[70:73], v[200:203], v[46:49]
	v_mfma_i32_16x16x64_i8 v[42:45], v[78:81], v[200:203], v[42:45]
	v_mfma_i32_16x16x64_i8 v[30:33], v[70:73], v[208:211], v[30:33]
	v_mfma_i32_16x16x64_i8 v[26:29], v[78:81], v[208:211], v[26:29]
	v_mfma_i32_16x16x64_i8 v[14:17], v[70:73], v[216:219], v[14:17]
	v_mfma_i32_16x16x64_i8 v[10:13], v[78:81], v[216:219], v[10:13]
	v_mfma_i32_16x16x64_i8 v[54:57], v[146:149], v[188:191], v[54:57]
	v_mfma_i32_16x16x64_i8 v[50:53], v[174:177], v[188:191], v[50:53]
	v_mfma_i32_16x16x64_i8 v[38:41], v[146:149], v[196:199], v[38:41]
	v_mfma_i32_16x16x64_i8 v[34:37], v[174:177], v[196:199], v[34:37]
	v_mfma_i32_16x16x64_i8 v[22:25], v[146:149], v[204:207], v[22:25]
	v_mfma_i32_16x16x64_i8 v[18:21], v[174:177], v[204:207], v[18:21]
	v_mfma_i32_16x16x64_i8 v[6:9], v[146:149], v[212:215], v[6:9]
	v_mfma_i32_16x16x64_i8 v[2:5], v[174:177], v[212:215], v[2:5]
	v_mfma_i32_16x16x64_i8 v[54:57], v[150:153], v[192:195], v[54:57]
	v_mfma_i32_16x16x64_i8 v[50:53], v[184:187], v[192:195], v[50:53]
	v_mfma_i32_16x16x64_i8 v[38:41], v[150:153], v[200:203], v[38:41]
	v_mfma_i32_16x16x64_i8 v[34:37], v[184:187], v[200:203], v[34:37]
	v_mfma_i32_16x16x64_i8 v[22:25], v[150:153], v[208:211], v[22:25]
	v_mfma_i32_16x16x64_i8 v[18:21], v[184:187], v[208:211], v[18:21]
	v_mfma_i32_16x16x64_i8 v[6:9], v[150:153], v[216:219], v[6:9]
	v_mfma_i32_16x16x64_i8 v[2:5], v[184:187], v[216:219], v[2:5]
	s_barrier
; #define PG8_STAGE(bufoff, gbase, voff) do { _Pragma("unroll") for (int _i = 0; _i < 2; ++_i) \
;         __builtin_amdgcn_global_load_lds((const unsigned*)((const char*)(gbase) + (voff)[_i]), (LAS unsigned*)(lds + (bufoff) + ldsw + _i * 8192), 16, 0, 0); } while (0)
; #define PG8_LDA(dst, b, h) do { _Pragma("unroll") for (int m = 0; m < 4; ++m) _Pragma("unroll") for (int k = 0; k < 2; ++k) dst[m][k] = *(const LAS bf16x8*)(lds + PG8_SA(b, h) + aoff + m * 2048 + k * 1024); } while (0)
; #define PG8_LDB(dst, b, h) do { _Pragma("unroll") for (int n = 0; n < 2; ++n) _Pragma("unroll") for (int k = 0; k < 2; ++k) dst[n][k] = *(const LAS bf16x8*)(lds + PG8_SB(b, h) + boff + n * 2048 + k * 1024); } while (0)
; #define PG8_WAIT_V(n) asm volatile("s_waitcnt vmcnt(" #n ")" ::: "memory")
; #define PG8_WAIT_L(n) asm volatile("s_waitcnt lgkmcnt(" #n ")" ::: "memory")
; #define PG8_BAR __builtin_amdgcn_s_barrier()
; #define PG8_SCHED __builtin_amdgcn_sched_barrier(0)
; template <class Epi, class Sched, bool I8 = false>
; __device__ __forceinline__ void gemm_phase(LAS unsigned char* lds, const Gemm g, const Sched& S, const Epi& E) {
;     ...
;             PG8_LDB(B0, 1, 0); PG8_LDB(B1, 1, 1); PG8_SCHED; PG8_LDA(At, 1, 0); PG8_STAGE(PG8_SA(0, 1), a2 + hstepA, voffA);
;             PG8_WAIT_V(8); PG8_WAIT_L(0); PG8_BAR; PG8_MMA(0, 0, At, B0); PG8_MMA(0, 1, At, B1); PG8_BAR; PG8_SCHED;
;             PG8_LDA(At, 1, 1); PG8_STAGE(PG8_SB(1, 0), b3, voffB); PG8_STAGE(PG8_SB(1, 1), b3 + hstepB, voffB); PG8_STAGE(PG8_SA(1, 0), a3, voffA);
;             PG8_WAIT_V(8); PG8_WAIT_L(0); PG8_BAR; PG8_MMA(1, 0, At, B0); PG8_MMA(1, 1, At, B1); PG8_BAR; PG8_SCHED;
;         }
	s_add_i32 s50, 0, 0x18000
	s_add_i32 s51, 0, 0x1c000
	v_add_u32_e32 v78, s50, v178
	v_add_u32_e32 v164, s51, v178
	ds_read_b128 v[66:69], v78
	ds_read_b128 v[70:73], v78 offset:1024
	ds_read_b128 v[74:77], v78 offset:2048
	ds_read_b128 v[78:81], v78 offset:3072
	ds_read_b128 v[146:149], v164
	ds_read_b128 v[150:153], v164 offset:1024
	ds_read_b128 v[174:177], v164 offset:2048
	ds_read_b128 v[184:187], v164 offset:3072
	ds_read_b128 v[188:191], v182 offset:32768
	ds_read_b128 v[192:195], v182 offset:33792
	ds_read_b128 v[196:199], v182 offset:34816
	ds_read_b128 v[200:203], v182 offset:35840
	ds_read_b128 v[204:207], v182 offset:36864
	ds_read_b128 v[208:211], v182 offset:37888
	ds_read_b128 v[212:215], v182 offset:38912
	ds_read_b128 v[216:219], v182 offset:39936
	s_mov_b32 m0, s31
	s_nop 0
	global_load_lds_dwordx4 v156, s[24:25]
	s_mov_b32 m0, s33
	s_nop 0
	global_load_lds_dwordx4 v160, s[24:25]
	s_add_u32 s24, s24, 0x4000
	s_addc_u32 s25, s25, 0
	s_mov_b32 m0, s34
	s_nop 0
	global_load_lds_dwordx4 v156, s[24:25]
	s_mov_b32 m0, s35
	s_nop 0
	global_load_lds_dwordx4 v160, s[24:25]
	s_waitcnt vmcnt(8)
	s_waitcnt lgkmcnt(0)
	s_barrier
	s_waitcnt lgkmcnt(0)
	v_mfma_i32_16x16x64_i8 v[142:145], v[66:69], v[188:191], v[142:145]
	v_mfma_i32_16x16x64_i8 v[138:141], v[74:77], v[188:191], v[138:141]
	v_mfma_i32_16x16x64_i8 v[126:129], v[66:69], v[196:199], v[126:129]
	v_mfma_i32_16x16x64_i8 v[122:125], v[74:77], v[196:199], v[122:125]
	v_mfma_i32_16x16x64_i8 v[110:113], v[66:69], v[204:207], v[110:113]
	v_mfma_i32_16x16x64_i8 v[106:109], v[74:77], v[204:207], v[106:109]
	v_mfma_i32_16x16x64_i8 v[94:97], v[66:69], v[212:215], v[94:97]
	v_mfma_i32_16x16x64_i8 v[90:93], v[74:77], v[212:215], v[90:93]
	v_mfma_i32_16x16x64_i8 v[142:145], v[70:73], v[192:195], v[142:145]
	v_mfma_i32_16x16x64_i8 v[138:141], v[78:81], v[192:195], v[138:141]
	v_mfma_i32_16x16x64_i8 v[126:129], v[70:73], v[200:203], v[126:129]
	v_mfma_i32_16x16x64_i8 v[122:125], v[78:81], v[200:203], v[122:125]
	v_mfma_i32_16x16x64_i8 v[110:113], v[70:73], v[208:211], v[110:113]
	v_mfma_i32_16x16x64_i8 v[106:109], v[78:81], v[208:211], v[106:109]
	v_mfma_i32_16x16x64_i8 v[94:97], v[70:73], v[216:219], v[94:97]
	v_mfma_i32_16x16x64_i8 v[90:93], v[78:81], v[216:219], v[90:93]
	v_mfma_i32_16x16x64_i8 v[134:137], v[146:149], v[188:191], v[134:137]
	v_mfma_i32_16x16x64_i8 v[130:133], v[174:177], v[188:191], v[130:133]
	v_mfma_i32_16x16x64_i8 v[118:121], v[146:149], v[196:199], v[118:121]
	v_mfma_i32_16x16x64_i8 v[114:117], v[174:177], v[196:199], v[114:117]
	v_mfma_i32_16x16x64_i8 v[102:105], v[146:149], v[204:207], v[102:105]
	v_mfma_i32_16x16x64_i8 v[98:101], v[174:177], v[204:207], v[98:101]
	v_mfma_i32_16x16x64_i8 v[86:89], v[146:149], v[212:215], v[86:89]
	v_mfma_i32_16x16x64_i8 v[82:85], v[174:177], v[212:215], v[82:85]
	v_mfma_i32_16x16x64_i8 v[134:137], v[150:153], v[192:195], v[134:137]
	v_mfma_i32_16x16x64_i8 v[130:133], v[184:187], v[192:195], v[130:133]
	v_mfma_i32_16x16x64_i8 v[118:121], v[150:153], v[200:203], v[118:121]
	v_mfma_i32_16x16x64_i8 v[114:117], v[184:187], v[200:203], v[114:117]
	v_mfma_i32_16x16x64_i8 v[102:105], v[150:153], v[208:211], v[102:105]
	v_mfma_i32_16x16x64_i8 v[98:101], v[184:187], v[208:211], v[98:101]
	v_mfma_i32_16x16x64_i8 v[86:89], v[150:153], v[216:219], v[86:89]
	v_mfma_i32_16x16x64_i8 v[82:85], v[184:187], v[216:219], v[82:85]
	s_barrier
	s_add_u32 s24, s22, 0x8000
	s_addc_u32 s25, s23, 0
	s_add_i32 s50, s50, s30
	s_mov_b32 m0, s50
	ds_read_b128 v[188:191], v182 offset:49152
	ds_read_b128 v[192:195], v182 offset:50176
	ds_read_b128 v[196:199], v182 offset:51200
	ds_read_b128 v[200:203], v182 offset:52224
	ds_read_b128 v[204:207], v182 offset:53248
	ds_read_b128 v[208:211], v182 offset:54272
	ds_read_b128 v[212:215], v182 offset:55296
	ds_read_b128 v[216:219], v182 offset:56320
	global_load_lds_dwordx4 v158, s[24:25]
	s_add_i32 m0, s50, 0x2000
	s_add_u32 s22, s22, 0xc000
	v_lshl_add_u64 v[220:221], s[24:25], 0, v[162:163]
	s_addc_u32 s23, s23, 0
	s_add_i32 s24, s51, s30
	global_load_lds_dwordx4 v[220:221], off
	s_mov_b32 m0, s24
	s_nop 0
	global_load_lds_dwordx4 v158, s[22:23]
	s_add_i32 m0, s24, 0x2000
	s_nop 0
	global_load_lds_dwordx4 v162, s[22:23]
	s_waitcnt vmcnt(6)
	s_waitcnt lgkmcnt(0)
	s_barrier
	s_waitcnt lgkmcnt(0)
	v_mfma_i32_16x16x64_i8 v[62:65], v[66:69], v[188:191], v[62:65]
	v_mfma_i32_16x16x64_i8 v[58:61], v[74:77], v[188:191], v[58:61]
	v_mfma_i32_16x16x64_i8 v[46:49], v[66:69], v[196:199], v[46:49]
	v_mfma_i32_16x16x64_i8 v[42:45], v[74:77], v[196:199], v[42:45]
	v_mfma_i32_16x16x64_i8 v[30:33], v[66:69], v[204:207], v[30:33]
	v_mfma_i32_16x16x64_i8 v[26:29], v[74:77], v[204:207], v[26:29]
	v_mfma_i32_16x16x64_i8 v[14:17], v[66:69], v[212:215], v[14:17]
	v_mfma_i32_16x16x64_i8 v[10:13], v[74:77], v[212:215], v[10:13]
	v_mfma_i32_16x16x64_i8 v[62:65], v[70:73], v[192:195], v[62:65]
	v_mfma_i32_16x16x64_i8 v[58:61], v[78:81], v[192:195], v[58:61]
	v_mfma_i32_16x16x64_i8 v[46:49], v[70:73], v[200:203], v[46:49]
	v_mfma_i32_16x16x64_i8 v[42:45], v[78:81], v[200:203], v[42:45]
	v_mfma_i32_16x16x64_i8 v[30:33], v[70:73], v[208:211], v[30:33]
	v_mfma_i32_16x16x64_i8 v[26:29], v[78:81], v[208:211], v[26:29]
	v_mfma_i32_16x16x64_i8 v[14:17], v[70:73], v[216:219], v[14:17]
	v_mfma_i32_16x16x64_i8 v[10:13], v[78:81], v[216:219], v[10:13]
	v_mfma_i32_16x16x64_i8 v[54:57], v[146:149], v[188:191], v[54:57]
	v_mfma_i32_16x16x64_i8 v[50:53], v[174:177], v[188:191], v[50:53]
	v_mfma_i32_16x16x64_i8 v[38:41], v[146:149], v[196:199], v[38:41]
	v_mfma_i32_16x16x64_i8 v[34:37], v[174:177], v[196:199], v[34:37]
	v_mfma_i32_16x16x64_i8 v[22:25], v[146:149], v[204:207], v[22:25]
	v_mfma_i32_16x16x64_i8 v[18:21], v[174:177], v[204:207], v[18:21]
	v_mfma_i32_16x16x64_i8 v[6:9], v[146:149], v[212:215], v[6:9]
	v_mfma_i32_16x16x64_i8 v[2:5], v[174:177], v[212:215], v[2:5]
	v_mfma_i32_16x16x64_i8 v[54:57], v[150:153], v[192:195], v[54:57]
	v_mfma_i32_16x16x64_i8 v[50:53], v[184:187], v[192:195], v[50:53]
	v_mfma_i32_16x16x64_i8 v[38:41], v[150:153], v[200:203], v[38:41]
	v_mfma_i32_16x16x64_i8 v[34:37], v[184:187], v[200:203], v[34:37]
	v_mfma_i32_16x16x64_i8 v[22:25], v[150:153], v[208:211], v[22:25]
	v_mfma_i32_16x16x64_i8 v[18:21], v[184:187], v[208:211], v[18:21]
	v_mfma_i32_16x16x64_i8 v[6:9], v[150:153], v[216:219], v[6:9]
	v_mfma_i32_16x16x64_i8 v[2:5], v[184:187], v[216:219], v[2:5]
	s_barrier
	s_add_i32 s49, s49, 2
	s_add_u32 s18, s18, 0x10000
	s_addc_u32 s19, s19, 0
	s_add_u32 s47, s47, 0x10000
	s_addc_u32 s48, s48, 0
	s_cmpk_gt_u32 s49, 0x53
	s_cbranch_scc0 .LBB0_1393
	s_and_b64 vcc, exec, s[14:15]
	s_cbranch_vccz .LBB0_1396
	s_barrier

; #define PG8_STAGE(bufoff, gbase, voff) do { _Pragma("unroll") for (int _i = 0; _i < 2; ++_i) \
;         __builtin_amdgcn_global_load_lds((const unsigned*)((const char*)(gbase) + (voff)[_i]), (LAS unsigned*)(lds + (bufoff) + ldsw + _i * 8192), 16, 0, 0); } while (0)
; #define PG8_LDA(dst, b, h) do { _Pragma("unroll") for (int m = 0; m < 4; ++m) _Pragma("unroll") for (int k = 0; k < 2; ++k) dst[m][k] = *(const LAS bf16x8*)(lds + PG8_SA(b, h) + aoff + m * 2048 + k * 1024); } while (0)
; #define PG8_LDB(dst, b, h) do { _Pragma("unroll") for (int n = 0; n < 2; ++n) _Pragma("unroll") for (int k = 0; k < 2; ++k) dst[n][k] = *(const LAS bf16x8*)(lds + PG8_SB(b, h) + boff + n * 2048 + k * 1024); } while (0)
; #define PG8_WAIT_V(n) asm volatile("s_waitcnt vmcnt(" #n ")" ::: "memory")
; #define PG8_WAIT_L(n) asm volatile("s_waitcnt lgkmcnt(" #n ")" ::: "memory")
; #define PG8_BAR __builtin_amdgcn_s_barrier()
; #define PG8_SCHED __builtin_amdgcn_sched_barrier(0)
; template <class Epi, class Sched, bool I8 = false>
; __device__ __forceinline__ void gemm_phase(LAS unsigned char* lds, const Gemm g, const Sched& S, const Epi& E) {
;     ...
;             PG8_LDB(B0, 0, 0); PG8_LDB(B1, 0, 1); PG8_SCHED; PG8_LDA(At, 0, 0); PG8_STAGE(PG8_SA(1, 1), a1 + hstepA, voffA);
;             PG8_WAIT_V(8); PG8_WAIT_L(0); PG8_BAR; PG8_MMA(0, 0, At, B0); PG8_MMA(0, 1, At, B1); PG8_BAR; PG8_SCHED;
;             PG8_LDA(At, 0, 1); PG8_STAGE(PG8_SB(0, 0), b2, voffB); PG8_STAGE(PG8_SB(0, 1), b2 + hstepB, voffB); PG8_STAGE(PG8_SA(0, 0), a2, voffA);
;             PG8_WAIT_V(8); PG8_WAIT_L(0); PG8_BAR; PG8_MMA(1, 0, At, B0); PG8_MMA(1, 1, At, B1); PG8_BAR; PG8_SCHED;
.LBB0_1482:
	ds_read_b128 v[152:155], v182
	ds_read_b128 v[156:159], v182 offset:1024
	ds_read_b128 v[160:163], v182 offset:2048
	ds_read_b128 v[164:167], v182 offset:3072
	ds_read_b128 v[168:171], v183
	ds_read_b128 v[172:175], v183 offset:1024
	ds_read_b128 v[176:179], v183 offset:2048
	ds_read_b128 v[186:189], v183 offset:3072
	s_add_u32 s38, s8, 0x4000
	s_addc_u32 s39, s9, 0
	s_cmp_eq_u32 s47, 60
	s_cselect_b32 s42, s31, s38
	s_cselect_b32 s43, s7, s39
	s_cselect_b32 s40, s44, s45
	s_cselect_b32 s41, s29, s46
	s_add_u32 s38, s42, 0x8000
	s_addc_u32 s39, s43, 0
	s_sub_u32 s98, s8, 0x4000
	s_subb_u32 s99, s9, 0
	ds_read_b128 v[190:193], v184
	ds_read_b128 v[194:197], v184 offset:1024
	ds_read_b128 v[198:201], v184 offset:2048
	ds_read_b128 v[202:205], v184 offset:3072
	ds_read_b128 v[206:209], v184 offset:4096
	ds_read_b128 v[210:213], v184 offset:5120
	ds_read_b128 v[214:217], v184 offset:6144
	ds_read_b128 v[218:221], v184 offset:7168
	s_mov_b32 m0, s58
	s_nop 0
	global_load_lds_dwordx4 v130, s[98:99]
	s_mov_b32 m0, s59
	s_nop 0
	global_load_lds_dwordx4 v134, s[98:99]
	s_add_i32 m0, s33, 0xc000
	s_nop 0
	global_load_lds_dwordx4 v144, s[8:9]
	s_add_i32 m0, s33, 0xe000
	s_nop 0
	global_load_lds_dwordx4 v146, s[8:9]
	s_waitcnt vmcnt(8)
	s_waitcnt lgkmcnt(0)
	s_barrier
	s_waitcnt lgkmcnt(0)
	v_mfma_f32_16x16x32_bf16 v[126:129], v[152:155], v[190:193], v[126:129]
	v_mfma_f32_16x16x32_bf16 v[122:125], v[160:163], v[190:193], v[122:125]
	v_mfma_f32_16x16x32_bf16 v[110:113], v[152:155], v[198:201], v[110:113]
	v_mfma_f32_16x16x32_bf16 v[106:109], v[160:163], v[198:201], v[106:109]
	v_mfma_f32_16x16x32_bf16 v[94:97], v[152:155], v[206:209], v[94:97]
	v_mfma_f32_16x16x32_bf16 v[90:93], v[160:163], v[206:209], v[90:93]
	v_mfma_f32_16x16x32_bf16 v[78:81], v[152:155], v[214:217], v[78:81]
	v_mfma_f32_16x16x32_bf16 v[74:77], v[160:163], v[214:217], v[74:77]
	v_mfma_f32_16x16x32_bf16 v[126:129], v[156:159], v[194:197], v[126:129]
	v_mfma_f32_16x16x32_bf16 v[122:125], v[164:167], v[194:197], v[122:125]
	v_mfma_f32_16x16x32_bf16 v[110:113], v[156:159], v[202:205], v[110:113]
	v_mfma_f32_16x16x32_bf16 v[106:109], v[164:167], v[202:205], v[106:109]
	v_mfma_f32_16x16x32_bf16 v[94:97], v[156:159], v[210:213], v[94:97]
	v_mfma_f32_16x16x32_bf16 v[90:93], v[164:167], v[210:213], v[90:93]
	v_mfma_f32_16x16x32_bf16 v[78:81], v[156:159], v[218:221], v[78:81]
	v_mfma_f32_16x16x32_bf16 v[74:77], v[164:167], v[218:221], v[74:77]
	v_mfma_f32_16x16x32_bf16 v[118:121], v[168:171], v[190:193], v[118:121]
	v_mfma_f32_16x16x32_bf16 v[114:117], v[176:179], v[190:193], v[114:117]
	v_mfma_f32_16x16x32_bf16 v[102:105], v[168:171], v[198:201], v[102:105]
	v_mfma_f32_16x16x32_bf16 v[98:101], v[176:179], v[198:201], v[98:101]
	v_mfma_f32_16x16x32_bf16 v[86:89], v[168:171], v[206:209], v[86:89]
	v_mfma_f32_16x16x32_bf16 v[82:85], v[176:179], v[206:209], v[82:85]
	v_mfma_f32_16x16x32_bf16 v[70:73], v[168:171], v[214:217], v[70:73]
	v_mfma_f32_16x16x32_bf16 v[66:69], v[176:179], v[214:217], v[66:69]
	v_mfma_f32_16x16x32_bf16 v[118:121], v[172:175], v[194:197], v[118:121]
	v_mfma_f32_16x16x32_bf16 v[114:117], v[186:189], v[194:197], v[114:117]
	v_mfma_f32_16x16x32_bf16 v[102:105], v[172:175], v[202:205], v[102:105]
	v_mfma_f32_16x16x32_bf16 v[98:101], v[186:189], v[202:205], v[98:101]
	v_mfma_f32_16x16x32_bf16 v[86:89], v[172:175], v[210:213], v[86:89]
	v_mfma_f32_16x16x32_bf16 v[82:85], v[186:189], v[210:213], v[82:85]
	v_mfma_f32_16x16x32_bf16 v[70:73], v[172:175], v[218:221], v[70:73]
	v_mfma_f32_16x16x32_bf16 v[66:69], v[186:189], v[218:221], v[66:69]
	s_barrier
	s_add_i32 s48, s63, s25
	s_mov_b32 m0, s48
	ds_read_b128 v[190:193], v184 offset:16384
	ds_read_b128 v[194:197], v184 offset:17408
	ds_read_b128 v[198:201], v184 offset:18432
	ds_read_b128 v[202:205], v184 offset:19456
	ds_read_b128 v[206:209], v184 offset:20480
	ds_read_b128 v[210:213], v184 offset:21504
	ds_read_b128 v[214:217], v184 offset:22528
	ds_read_b128 v[218:221], v184 offset:23552
	global_load_lds_dwordx4 v132, s[40:41]
	s_add_i32 m0, s48, 0x2000
	s_add_u32 s48, s40, 0x4000
	s_addc_u32 s49, s41, 0
	s_add_i32 s50, s64, s25
	global_load_lds_dwordx4 v136, s[40:41]
	s_mov_b32 m0, s50
	s_nop 0
	global_load_lds_dwordx4 v132, s[48:49]
	s_add_i32 m0, s50, 0x2000
	s_nop 0
	global_load_lds_dwordx4 v136, s[48:49]
	s_waitcnt vmcnt(6)
	s_waitcnt lgkmcnt(0)
	s_barrier
	s_waitcnt lgkmcnt(0)
	v_mfma_f32_16x16x32_bf16 v[62:65], v[152:155], v[190:193], v[62:65]
	v_mfma_f32_16x16x32_bf16 v[58:61], v[160:163], v[190:193], v[58:61]
	v_mfma_f32_16x16x32_bf16 v[46:49], v[152:155], v[198:201], v[46:49]
	v_mfma_f32_16x16x32_bf16 v[42:45], v[160:163], v[198:201], v[42:45]
	v_mfma_f32_16x16x32_bf16 v[30:33], v[152:155], v[206:209], v[30:33]
	v_mfma_f32_16x16x32_bf16 v[26:29], v[160:163], v[206:209], v[26:29]
	v_mfma_f32_16x16x32_bf16 v[14:17], v[152:155], v[214:217], v[14:17]
	v_mfma_f32_16x16x32_bf16 v[10:13], v[160:163], v[214:217], v[10:13]
	v_mfma_f32_16x16x32_bf16 v[62:65], v[156:159], v[194:197], v[62:65]
	v_mfma_f32_16x16x32_bf16 v[58:61], v[164:167], v[194:197], v[58:61]
	v_mfma_f32_16x16x32_bf16 v[46:49], v[156:159], v[202:205], v[46:49]
	v_mfma_f32_16x16x32_bf16 v[42:45], v[164:167], v[202:205], v[42:45]
	v_mfma_f32_16x16x32_bf16 v[30:33], v[156:159], v[210:213], v[30:33]
	v_mfma_f32_16x16x32_bf16 v[26:29], v[164:167], v[210:213], v[26:29]
	v_mfma_f32_16x16x32_bf16 v[14:17], v[156:159], v[218:221], v[14:17]
	v_mfma_f32_16x16x32_bf16 v[10:13], v[164:167], v[218:221], v[10:13]
	v_mfma_f32_16x16x32_bf16 v[54:57], v[168:171], v[190:193], v[54:57]
	v_mfma_f32_16x16x32_bf16 v[50:53], v[176:179], v[190:193], v[50:53]
	v_mfma_f32_16x16x32_bf16 v[38:41], v[168:171], v[198:201], v[38:41]
	v_mfma_f32_16x16x32_bf16 v[34:37], v[176:179], v[198:201], v[34:37]
	v_mfma_f32_16x16x32_bf16 v[22:25], v[168:171], v[206:209], v[22:25]
	v_mfma_f32_16x16x32_bf16 v[18:21], v[176:179], v[206:209], v[18:21]
	v_mfma_f32_16x16x32_bf16 v[6:9], v[168:171], v[214:217], v[6:9]
	v_mfma_f32_16x16x32_bf16 v[2:5], v[176:179], v[214:217], v[2:5]
	v_mfma_f32_16x16x32_bf16 v[54:57], v[172:175], v[194:197], v[54:57]
	v_mfma_f32_16x16x32_bf16 v[50:53], v[186:189], v[194:197], v[50:53]
	v_mfma_f32_16x16x32_bf16 v[38:41], v[172:175], v[202:205], v[38:41]
	v_mfma_f32_16x16x32_bf16 v[34:37], v[186:189], v[202:205], v[34:37]
	v_mfma_f32_16x16x32_bf16 v[22:25], v[172:175], v[210:213], v[22:25]
	v_mfma_f32_16x16x32_bf16 v[18:21], v[186:189], v[210:213], v[18:21]
	v_mfma_f32_16x16x32_bf16 v[6:9], v[172:175], v[218:221], v[6:9]
	v_mfma_f32_16x16x32_bf16 v[2:5], v[186:189], v[218:221], v[2:5]
	s_barrier
; #define PG8_STAGE(bufoff, gbase, voff) do { _Pragma("unroll") for (int _i = 0; _i < 2; ++_i) \
;         __builtin_amdgcn_global_load_lds((const unsigned*)((const char*)(gbase) + (voff)[_i]), (LAS unsigned*)(lds + (bufoff) + ldsw + _i * 8192), 16, 0, 0); } while (0)
; #define PG8_LDA(dst, b, h) do { _Pragma("unroll") for (int m = 0; m < 4; ++m) _Pragma("unroll") for (int k = 0; k < 2; ++k) dst[m][k] = *(const LAS bf16x8*)(lds + PG8_SA(b, h) + aoff + m * 2048 + k * 1024); } while (0)
; #define PG8_LDB(dst, b, h) do { _Pragma("unroll") for (int n = 0; n < 2; ++n) _Pragma("unroll") for (int k = 0; k < 2; ++k) dst[n][k] = *(const LAS bf16x8*)(lds + PG8_SB(b, h) + boff + n * 2048 + k * 1024); } while (0)
; #define PG8_WAIT_V(n) asm volatile("s_waitcnt vmcnt(" #n ")" ::: "memory")
; #define PG8_WAIT_L(n) asm volatile("s_waitcnt lgkmcnt(" #n ")" ::: "memory")
; #define PG8_BAR __builtin_amdgcn_s_barrier()
; #define PG8_SCHED __builtin_amdgcn_sched_barrier(0)
; template <class Epi, class Sched, bool I8 = false>
; __device__ __forceinline__ void gemm_phase(LAS unsigned char* lds, const Gemm g, const Sched& S, const Epi& E) {
;     ...
;             PG8_LDB(B0, 1, 0); PG8_LDB(B1, 1, 1); PG8_SCHED; PG8_LDA(At, 1, 0); PG8_STAGE(PG8_SA(0, 1), a2 + hstepA, voffA);
;             PG8_WAIT_V(8); PG8_WAIT_L(0); PG8_BAR; PG8_MMA(0, 0, At, B0); PG8_MMA(0, 1, At, B1); PG8_BAR; PG8_SCHED;
;             PG8_LDA(At, 1, 1); PG8_STAGE(PG8_SB(1, 0), b3, voffB); PG8_STAGE(PG8_SB(1, 1), b3 + hstepB, voffB); PG8_STAGE(PG8_SA(1, 0), a3, voffA);
;             PG8_WAIT_V(8); PG8_WAIT_L(0); PG8_BAR; PG8_MMA(1, 0, At, B0); PG8_MMA(1, 1, At, B1); PG8_BAR; PG8_SCHED;
;         }
	s_add_i32 s48, 0, 0x18000
	v_add_u32_e32 v138, s48, v181
	s_add_i32 s49, 0, 0x1c000
	ds_read_b128 v[152:155], v138
	ds_read_b128 v[156:159], v138 offset:1024
	ds_read_b128 v[160:163], v138 offset:2048
	ds_read_b128 v[164:167], v138 offset:3072
	v_add_u32_e32 v138, s49, v181
	ds_read_b128 v[168:171], v138
	ds_read_b128 v[172:175], v138 offset:1024
	ds_read_b128 v[176:179], v138 offset:2048
	ds_read_b128 v[186:189], v138 offset:3072
	ds_read_b128 v[190:193], v184 offset:32768
	ds_read_b128 v[194:197], v184 offset:33792
	ds_read_b128 v[198:201], v184 offset:34816
	ds_read_b128 v[202:205], v184 offset:35840
	ds_read_b128 v[206:209], v184 offset:36864
	ds_read_b128 v[210:213], v184 offset:37888
	ds_read_b128 v[214:217], v184 offset:38912
	ds_read_b128 v[218:221], v184 offset:39936
	s_mov_b32 m0, s33
	s_nop 0
	global_load_lds_dwordx4 v130, s[42:43]
	s_mov_b32 m0, s52
	s_nop 0
	global_load_lds_dwordx4 v134, s[42:43]
	s_add_u32 s42, s42, 0x4000
	s_addc_u32 s43, s43, 0
	s_mov_b32 m0, s53
	s_nop 0
	global_load_lds_dwordx4 v130, s[42:43]
	s_mov_b32 m0, s54
	s_nop 0
	global_load_lds_dwordx4 v134, s[42:43]
	s_waitcnt vmcnt(8)
	s_waitcnt lgkmcnt(0)
	s_barrier
	s_waitcnt lgkmcnt(0)
	v_mfma_f32_16x16x32_bf16 v[126:129], v[152:155], v[190:193], v[126:129]
	v_mfma_f32_16x16x32_bf16 v[122:125], v[160:163], v[190:193], v[122:125]
	v_mfma_f32_16x16x32_bf16 v[110:113], v[152:155], v[198:201], v[110:113]
	v_mfma_f32_16x16x32_bf16 v[106:109], v[160:163], v[198:201], v[106:109]
	v_mfma_f32_16x16x32_bf16 v[94:97], v[152:155], v[206:209], v[94:97]
	v_mfma_f32_16x16x32_bf16 v[90:93], v[160:163], v[206:209], v[90:93]
	v_mfma_f32_16x16x32_bf16 v[78:81], v[152:155], v[214:217], v[78:81]
	v_mfma_f32_16x16x32_bf16 v[74:77], v[160:163], v[214:217], v[74:77]
	v_mfma_f32_16x16x32_bf16 v[126:129], v[156:159], v[194:197], v[126:129]
	v_mfma_f32_16x16x32_bf16 v[122:125], v[164:167], v[194:197], v[122:125]
	v_mfma_f32_16x16x32_bf16 v[110:113], v[156:159], v[202:205], v[110:113]
	v_mfma_f32_16x16x32_bf16 v[106:109], v[164:167], v[202:205], v[106:109]
	v_mfma_f32_16x16x32_bf16 v[94:97], v[156:159], v[210:213], v[94:97]
	v_mfma_f32_16x16x32_bf16 v[90:93], v[164:167], v[210:213], v[90:93]
	v_mfma_f32_16x16x32_bf16 v[78:81], v[156:159], v[218:221], v[78:81]
	v_mfma_f32_16x16x32_bf16 v[74:77], v[164:167], v[218:221], v[74:77]
	v_mfma_f32_16x16x32_bf16 v[118:121], v[168:171], v[190:193], v[118:121]
	v_mfma_f32_16x16x32_bf16 v[114:117], v[176:179], v[190:193], v[114:117]
	v_mfma_f32_16x16x32_bf16 v[102:105], v[168:171], v[198:201], v[102:105]
	v_mfma_f32_16x16x32_bf16 v[98:101], v[176:179], v[198:201], v[98:101]
	v_mfma_f32_16x16x32_bf16 v[86:89], v[168:171], v[206:209], v[86:89]
	v_mfma_f32_16x16x32_bf16 v[82:85], v[176:179], v[206:209], v[82:85]
	v_mfma_f32_16x16x32_bf16 v[70:73], v[168:171], v[214:217], v[70:73]
	v_mfma_f32_16x16x32_bf16 v[66:69], v[176:179], v[214:217], v[66:69]
	v_mfma_f32_16x16x32_bf16 v[118:121], v[172:175], v[194:197], v[118:121]
	v_mfma_f32_16x16x32_bf16 v[114:117], v[186:189], v[194:197], v[114:117]
	v_mfma_f32_16x16x32_bf16 v[102:105], v[172:175], v[202:205], v[102:105]
	v_mfma_f32_16x16x32_bf16 v[98:101], v[186:189], v[202:205], v[98:101]
	v_mfma_f32_16x16x32_bf16 v[86:89], v[172:175], v[210:213], v[86:89]
	v_mfma_f32_16x16x32_bf16 v[82:85], v[186:189], v[210:213], v[82:85]
	v_mfma_f32_16x16x32_bf16 v[70:73], v[172:175], v[218:221], v[70:73]
	v_mfma_f32_16x16x32_bf16 v[66:69], v[186:189], v[218:221], v[66:69]
	s_barrier
	s_add_u32 s42, s40, 0x8000
	s_addc_u32 s43, s41, 0
	s_add_i32 s48, s48, s25
	s_mov_b32 m0, s48
	ds_read_b128 v[190:193], v184 offset:49152
	ds_read_b128 v[194:197], v184 offset:50176
	ds_read_b128 v[198:201], v184 offset:51200
	ds_read_b128 v[202:205], v184 offset:52224
	ds_read_b128 v[206:209], v184 offset:53248
	ds_read_b128 v[210:213], v184 offset:54272
	ds_read_b128 v[214:217], v184 offset:55296
	ds_read_b128 v[218:221], v184 offset:56320
	global_load_lds_dwordx4 v132, s[42:43]
	s_add_i32 m0, s48, 0x2000
	s_add_u32 s40, s40, 0xc000
	v_lshl_add_u64 v[222:223], s[42:43], 0, v[136:137]
	s_addc_u32 s41, s41, 0
	s_add_i32 s42, s49, s25
	global_load_lds_dwordx4 v[222:223], off
	s_mov_b32 m0, s42
	s_nop 0
	global_load_lds_dwordx4 v132, s[40:41]
	s_add_i32 m0, s42, 0x2000
	s_nop 0
	global_load_lds_dwordx4 v136, s[40:41]
	s_waitcnt vmcnt(6)
	s_waitcnt lgkmcnt(0)
	s_barrier
	s_waitcnt lgkmcnt(0)
	v_mfma_f32_16x16x32_bf16 v[62:65], v[152:155], v[190:193], v[62:65]
	v_mfma_f32_16x16x32_bf16 v[58:61], v[160:163], v[190:193], v[58:61]
	v_mfma_f32_16x16x32_bf16 v[46:49], v[152:155], v[198:201], v[46:49]
	v_mfma_f32_16x16x32_bf16 v[42:45], v[160:163], v[198:201], v[42:45]
	v_mfma_f32_16x16x32_bf16 v[30:33], v[152:155], v[206:209], v[30:33]
	v_mfma_f32_16x16x32_bf16 v[26:29], v[160:163], v[206:209], v[26:29]
	v_mfma_f32_16x16x32_bf16 v[14:17], v[152:155], v[214:217], v[14:17]
	v_mfma_f32_16x16x32_bf16 v[10:13], v[160:163], v[214:217], v[10:13]
	v_mfma_f32_16x16x32_bf16 v[62:65], v[156:159], v[194:197], v[62:65]
	v_mfma_f32_16x16x32_bf16 v[58:61], v[164:167], v[194:197], v[58:61]
	v_mfma_f32_16x16x32_bf16 v[46:49], v[156:159], v[202:205], v[46:49]
	v_mfma_f32_16x16x32_bf16 v[42:45], v[164:167], v[202:205], v[42:45]
	v_mfma_f32_16x16x32_bf16 v[30:33], v[156:159], v[210:213], v[30:33]
	v_mfma_f32_16x16x32_bf16 v[26:29], v[164:167], v[210:213], v[26:29]
	v_mfma_f32_16x16x32_bf16 v[14:17], v[156:159], v[218:221], v[14:17]
	v_mfma_f32_16x16x32_bf16 v[10:13], v[164:167], v[218:221], v[10:13]
	v_mfma_f32_16x16x32_bf16 v[54:57], v[168:171], v[190:193], v[54:57]
	v_mfma_f32_16x16x32_bf16 v[50:53], v[176:179], v[190:193], v[50:53]
	v_mfma_f32_16x16x32_bf16 v[38:41], v[168:171], v[198:201], v[38:41]
	v_mfma_f32_16x16x32_bf16 v[34:37], v[176:179], v[198:201], v[34:37]
	v_mfma_f32_16x16x32_bf16 v[22:25], v[168:171], v[206:209], v[22:25]
	v_mfma_f32_16x16x32_bf16 v[18:21], v[176:179], v[206:209], v[18:21]
	v_mfma_f32_16x16x32_bf16 v[6:9], v[168:171], v[214:217], v[6:9]
	v_mfma_f32_16x16x32_bf16 v[2:5], v[176:179], v[214:217], v[2:5]
	v_mfma_f32_16x16x32_bf16 v[54:57], v[172:175], v[194:197], v[54:57]
	v_mfma_f32_16x16x32_bf16 v[50:53], v[186:189], v[194:197], v[50:53]
	v_mfma_f32_16x16x32_bf16 v[38:41], v[172:175], v[202:205], v[38:41]
	v_mfma_f32_16x16x32_bf16 v[34:37], v[186:189], v[202:205], v[34:37]
	v_mfma_f32_16x16x32_bf16 v[22:25], v[172:175], v[210:213], v[22:25]
	v_mfma_f32_16x16x32_bf16 v[18:21], v[186:189], v[210:213], v[18:21]
	v_mfma_f32_16x16x32_bf16 v[6:9], v[172:175], v[218:221], v[6:9]
	v_mfma_f32_16x16x32_bf16 v[2:5], v[186:189], v[218:221], v[2:5]
	s_barrier
	s_add_i32 s47, s47, 2
	s_add_u32 s8, s8, 0x10000
	s_addc_u32 s9, s9, 0
	s_add_u32 s45, s45, 0x10000
	s_addc_u32 s46, s46, 0
	s_cmp_gt_u32 s47, 61
	s_cbranch_scc0 .LBB0_1482
	s_and_b64 vcc, exec, s[20:21]
	s_cbranch_vccz .LBB0_1485
	s_barrier

; #define PG8_STAGE(bufoff, gbase, voff) do { _Pragma("unroll") for (int _i = 0; _i < 2; ++_i) \
;         __builtin_amdgcn_global_load_lds((const unsigned*)((const char*)(gbase) + (voff)[_i]), (LAS unsigned*)(lds + (bufoff) + ldsw + _i * 8192), 16, 0, 0); } while (0)
; #define PG8_LDA(dst, b, h) do { _Pragma("unroll") for (int m = 0; m < 4; ++m) _Pragma("unroll") for (int k = 0; k < 2; ++k) dst[m][k] = *(const LAS bf16x8*)(lds + PG8_SA(b, h) + aoff + m * 2048 + k * 1024); } while (0)
; #define PG8_LDB(dst, b, h) do { _Pragma("unroll") for (int n = 0; n < 2; ++n) _Pragma("unroll") for (int k = 0; k < 2; ++k) dst[n][k] = *(const LAS bf16x8*)(lds + PG8_SB(b, h) + boff + n * 2048 + k * 1024); } while (0)
; #define PG8_WAIT_V(n) asm volatile("s_waitcnt vmcnt(" #n ")" ::: "memory")
; #define PG8_WAIT_L(n) asm volatile("s_waitcnt lgkmcnt(" #n ")" ::: "memory")
; #define PG8_BAR __builtin_amdgcn_s_barrier()
; #define PG8_SCHED __builtin_amdgcn_sched_barrier(0)
; template <class Epi, class Sched, bool I8 = false>
; __device__ __forceinline__ void gemm_phase(LAS unsigned char* lds, const Gemm g, const Sched& S, const Epi& E) {
;     ...
;             const char* a1 = cA + (size_t)(t + 1) * kstep;
;             const char* a2 = last ? nA : cA + (size_t)(t + 2) * kstep; const char* b2 = last ? nB : cB + (size_t)(t + 2) * kstep;
;             const char* a3 = a2 + kstep; const char* b3 = b2 + kstep;
;             PG8_LDB(B0, 0, 0); PG8_LDB(B1, 0, 1); PG8_SCHED; PG8_LDA(At, 0, 0); PG8_STAGE(PG8_SA(1, 1), a1 + hstepA, voffA);
;             PG8_WAIT_V(8); PG8_WAIT_L(0); PG8_BAR; PG8_MMA(0, 0, At, B0); PG8_MMA(0, 1, At, B1); PG8_BAR; PG8_SCHED;
;             PG8_LDA(At, 0, 1); PG8_STAGE(PG8_SB(0, 0), b2, voffB); PG8_STAGE(PG8_SB(0, 1), b2 + hstepB, voffB); PG8_STAGE(PG8_SA(0, 0), a2, voffA);
;             PG8_WAIT_V(8); PG8_WAIT_L(0); PG8_BAR; PG8_MMA(1, 0, At, B0); PG8_MMA(1, 1, At, B1); PG8_BAR; PG8_SCHED;
.LBB0_2685:
	ds_read_b128 v[130:133], v166
	ds_read_b128 v[134:137], v166 offset:1024
	ds_read_b128 v[158:161], v166 offset:2048
	ds_read_b128 v[170:173], v166 offset:3072
	ds_read_b128 v[174:177], v167
	ds_read_b128 v[178:181], v167 offset:1024
	ds_read_b128 v[182:185], v167 offset:2048
	ds_read_b128 v[186:189], v167 offset:3072
	s_add_u32 s12, s10, 0x4000
	s_addc_u32 s13, s11, 0
	s_cmp_eq_u32 s45, 4
	s_cselect_b32 s16, s40, s12
	s_cselect_b32 s17, s39, s13
	s_cselect_b32 s14, s42, s43
	s_cselect_b32 s15, s41, s44
	s_add_u32 s12, s16, 0x8000
	s_addc_u32 s13, s17, 0
	s_sub_u32 s98, s10, 0x4000
	s_subb_u32 s99, s11, 0
	ds_read_b128 v[190:193], v168
	ds_read_b128 v[194:197], v168 offset:1024
	ds_read_b128 v[198:201], v168 offset:2048
	ds_read_b128 v[202:205], v168 offset:3072
	ds_read_b128 v[206:209], v168 offset:4096
	ds_read_b128 v[210:213], v168 offset:5120
	ds_read_b128 v[214:217], v168 offset:6144
	ds_read_b128 v[218:221], v168 offset:7168
	s_mov_b32 m0, s33
	s_nop 0
	global_load_lds_dwordx4 v144, s[98:99]
	s_mov_b32 m0, s34
	s_nop 0
	global_load_lds_dwordx4 v140, s[98:99]
	s_add_i32 m0, s26, 0xc000
	s_nop 0
	global_load_lds_dwordx4 v150, s[10:11]
	s_add_i32 m0, s26, 0xe000
	s_nop 0
	global_load_lds_dwordx4 v152, s[10:11]
	s_waitcnt vmcnt(8)
	s_waitcnt lgkmcnt(0)
	s_barrier
	s_waitcnt lgkmcnt(0)
	v_mfma_f32_16x16x32_bf16 v[126:129], v[130:133], v[190:193], v[126:129]
	v_mfma_f32_16x16x32_bf16 v[122:125], v[158:161], v[190:193], v[122:125]
	v_mfma_f32_16x16x32_bf16 v[118:121], v[130:133], v[198:201], v[118:121]
	v_mfma_f32_16x16x32_bf16 v[114:117], v[158:161], v[198:201], v[114:117]
	v_mfma_f32_16x16x32_bf16 v[110:113], v[130:133], v[206:209], v[110:113]
	v_mfma_f32_16x16x32_bf16 v[106:109], v[158:161], v[206:209], v[106:109]
	v_mfma_f32_16x16x32_bf16 v[102:105], v[130:133], v[214:217], v[102:105]
	v_mfma_f32_16x16x32_bf16 v[98:101], v[158:161], v[214:217], v[98:101]
	v_mfma_f32_16x16x32_bf16 v[126:129], v[134:137], v[194:197], v[126:129]
	v_mfma_f32_16x16x32_bf16 v[122:125], v[170:173], v[194:197], v[122:125]
	v_mfma_f32_16x16x32_bf16 v[118:121], v[134:137], v[202:205], v[118:121]
	v_mfma_f32_16x16x32_bf16 v[114:117], v[170:173], v[202:205], v[114:117]
	v_mfma_f32_16x16x32_bf16 v[110:113], v[134:137], v[210:213], v[110:113]
	v_mfma_f32_16x16x32_bf16 v[106:109], v[170:173], v[210:213], v[106:109]
	v_mfma_f32_16x16x32_bf16 v[102:105], v[134:137], v[218:221], v[102:105]
	v_mfma_f32_16x16x32_bf16 v[98:101], v[170:173], v[218:221], v[98:101]
	v_mfma_f32_16x16x32_bf16 v[62:65], v[174:177], v[190:193], v[62:65]
	v_mfma_f32_16x16x32_bf16 v[58:61], v[182:185], v[190:193], v[58:61]
	v_mfma_f32_16x16x32_bf16 v[54:57], v[174:177], v[198:201], v[54:57]
	v_mfma_f32_16x16x32_bf16 v[50:53], v[182:185], v[198:201], v[50:53]
	v_mfma_f32_16x16x32_bf16 v[46:49], v[174:177], v[206:209], v[46:49]
	v_mfma_f32_16x16x32_bf16 v[42:45], v[182:185], v[206:209], v[42:45]
	v_mfma_f32_16x16x32_bf16 v[38:41], v[174:177], v[214:217], v[38:41]
	v_mfma_f32_16x16x32_bf16 v[34:37], v[182:185], v[214:217], v[34:37]
	v_mfma_f32_16x16x32_bf16 v[62:65], v[178:181], v[194:197], v[62:65]
	v_mfma_f32_16x16x32_bf16 v[58:61], v[186:189], v[194:197], v[58:61]
	v_mfma_f32_16x16x32_bf16 v[54:57], v[178:181], v[202:205], v[54:57]
	v_mfma_f32_16x16x32_bf16 v[50:53], v[186:189], v[202:205], v[50:53]
	v_mfma_f32_16x16x32_bf16 v[46:49], v[178:181], v[210:213], v[46:49]
	v_mfma_f32_16x16x32_bf16 v[42:45], v[186:189], v[210:213], v[42:45]
	v_mfma_f32_16x16x32_bf16 v[38:41], v[178:181], v[218:221], v[38:41]
	v_mfma_f32_16x16x32_bf16 v[34:37], v[186:189], v[218:221], v[34:37]
	s_barrier
	s_add_i32 s46, s62, s22
	s_mov_b32 m0, s46
	ds_read_b128 v[190:193], v168 offset:16384
	ds_read_b128 v[194:197], v168 offset:17408
	ds_read_b128 v[198:201], v168 offset:18432
	ds_read_b128 v[202:205], v168 offset:19456
	ds_read_b128 v[206:209], v168 offset:20480
	ds_read_b128 v[210:213], v168 offset:21504
	ds_read_b128 v[214:217], v168 offset:22528
	ds_read_b128 v[218:221], v168 offset:23552
	global_load_lds_dwordx4 v142, s[14:15]
	s_add_i32 m0, s46, 0x2000
	s_add_u32 s46, s14, 0x4000
	s_addc_u32 s47, s15, 0
	s_add_i32 s48, s35, s22
	global_load_lds_dwordx4 v138, s[14:15]
	s_mov_b32 m0, s48
	s_nop 0
	global_load_lds_dwordx4 v142, s[46:47]
	s_add_i32 m0, s48, 0x2000
	s_nop 0
	global_load_lds_dwordx4 v138, s[46:47]
	s_waitcnt vmcnt(6)
	s_waitcnt lgkmcnt(0)
	s_barrier
	s_waitcnt lgkmcnt(0)
	v_mfma_f32_16x16x32_bf16 v[94:97], v[130:133], v[190:193], v[94:97]
	v_mfma_f32_16x16x32_bf16 v[90:93], v[158:161], v[190:193], v[90:93]
	v_mfma_f32_16x16x32_bf16 v[86:89], v[130:133], v[198:201], v[86:89]
	v_mfma_f32_16x16x32_bf16 v[82:85], v[158:161], v[198:201], v[82:85]
	v_mfma_f32_16x16x32_bf16 v[78:81], v[130:133], v[206:209], v[78:81]
	v_mfma_f32_16x16x32_bf16 v[74:77], v[158:161], v[206:209], v[74:77]
	v_mfma_f32_16x16x32_bf16 v[70:73], v[130:133], v[214:217], v[70:73]
	v_mfma_f32_16x16x32_bf16 v[66:69], v[158:161], v[214:217], v[66:69]
	v_mfma_f32_16x16x32_bf16 v[94:97], v[134:137], v[194:197], v[94:97]
	v_mfma_f32_16x16x32_bf16 v[90:93], v[170:173], v[194:197], v[90:93]
	v_mfma_f32_16x16x32_bf16 v[86:89], v[134:137], v[202:205], v[86:89]
	v_mfma_f32_16x16x32_bf16 v[82:85], v[170:173], v[202:205], v[82:85]
	v_mfma_f32_16x16x32_bf16 v[78:81], v[134:137], v[210:213], v[78:81]
	v_mfma_f32_16x16x32_bf16 v[74:77], v[170:173], v[210:213], v[74:77]
	v_mfma_f32_16x16x32_bf16 v[70:73], v[134:137], v[218:221], v[70:73]
	v_mfma_f32_16x16x32_bf16 v[66:69], v[170:173], v[218:221], v[66:69]
	v_mfma_f32_16x16x32_bf16 v[30:33], v[174:177], v[190:193], v[30:33]
	v_mfma_f32_16x16x32_bf16 v[26:29], v[182:185], v[190:193], v[26:29]
	v_mfma_f32_16x16x32_bf16 v[22:25], v[174:177], v[198:201], v[22:25]
	v_mfma_f32_16x16x32_bf16 v[18:21], v[182:185], v[198:201], v[18:21]
	v_mfma_f32_16x16x32_bf16 v[14:17], v[174:177], v[206:209], v[14:17]
	v_mfma_f32_16x16x32_bf16 v[10:13], v[182:185], v[206:209], v[10:13]
	v_mfma_f32_16x16x32_bf16 v[6:9], v[174:177], v[214:217], v[6:9]
	v_mfma_f32_16x16x32_bf16 v[2:5], v[182:185], v[214:217], v[2:5]
	v_mfma_f32_16x16x32_bf16 v[30:33], v[178:181], v[194:197], v[30:33]
	v_mfma_f32_16x16x32_bf16 v[26:29], v[186:189], v[194:197], v[26:29]
	v_mfma_f32_16x16x32_bf16 v[22:25], v[178:181], v[202:205], v[22:25]
	v_mfma_f32_16x16x32_bf16 v[18:21], v[186:189], v[202:205], v[18:21]
	v_mfma_f32_16x16x32_bf16 v[14:17], v[178:181], v[210:213], v[14:17]
	v_mfma_f32_16x16x32_bf16 v[10:13], v[186:189], v[210:213], v[10:13]
	v_mfma_f32_16x16x32_bf16 v[6:9], v[178:181], v[218:221], v[6:9]
	v_mfma_f32_16x16x32_bf16 v[2:5], v[186:189], v[218:221], v[2:5]
	s_barrier
; #define PG8_STAGE(bufoff, gbase, voff) do { _Pragma("unroll") for (int _i = 0; _i < 2; ++_i) \
;         __builtin_amdgcn_global_load_lds((const unsigned*)((const char*)(gbase) + (voff)[_i]), (LAS unsigned*)(lds + (bufoff) + ldsw + _i * 8192), 16, 0, 0); } while (0)
; #define PG8_LDA(dst, b, h) do { _Pragma("unroll") for (int m = 0; m < 4; ++m) _Pragma("unroll") for (int k = 0; k < 2; ++k) dst[m][k] = *(const LAS bf16x8*)(lds + PG8_SA(b, h) + aoff + m * 2048 + k * 1024); } while (0)
; #define PG8_LDB(dst, b, h) do { _Pragma("unroll") for (int n = 0; n < 2; ++n) _Pragma("unroll") for (int k = 0; k < 2; ++k) dst[n][k] = *(const LAS bf16x8*)(lds + PG8_SB(b, h) + boff + n * 2048 + k * 1024); } while (0)
; #define PG8_WAIT_V(n) asm volatile("s_waitcnt vmcnt(" #n ")" ::: "memory")
; #define PG8_WAIT_L(n) asm volatile("s_waitcnt lgkmcnt(" #n ")" ::: "memory")
; #define PG8_BAR __builtin_amdgcn_s_barrier()
; #define PG8_SCHED __builtin_amdgcn_sched_barrier(0)
; template <class Epi, class Sched, bool I8 = false>
; __device__ __forceinline__ void gemm_phase(LAS unsigned char* lds, const Gemm g, const Sched& S, const Epi& E) {
;     ...
;             PG8_LDB(B0, 1, 0); PG8_LDB(B1, 1, 1); PG8_SCHED; PG8_LDA(At, 1, 0); PG8_STAGE(PG8_SA(0, 1), a2 + hstepA, voffA);
;             PG8_WAIT_V(8); PG8_WAIT_L(0); PG8_BAR; PG8_MMA(0, 0, At, B0); PG8_MMA(0, 1, At, B1); PG8_BAR; PG8_SCHED;
;             PG8_LDA(At, 1, 1); PG8_STAGE(PG8_SB(1, 0), b3, voffB); PG8_STAGE(PG8_SB(1, 1), b3 + hstepB, voffB); PG8_STAGE(PG8_SA(1, 0), a3, voffA);
;             PG8_WAIT_V(8); PG8_WAIT_L(0); PG8_BAR; PG8_MMA(1, 0, At, B0); PG8_MMA(1, 1, At, B1); PG8_BAR; PG8_SCHED;
;         }
	s_add_i32 s46, 0, 0x18000
	v_add_u32_e32 v155, s46, v165
	s_add_i32 s47, 0, 0x1c000
	ds_read_b128 v[130:133], v155
	ds_read_b128 v[134:137], v155 offset:1024
	ds_read_b128 v[158:161], v155 offset:2048
	ds_read_b128 v[170:173], v155 offset:3072
	v_add_u32_e32 v155, s47, v165
	ds_read_b128 v[174:177], v155
	ds_read_b128 v[178:181], v155 offset:1024
	ds_read_b128 v[182:185], v155 offset:2048
	ds_read_b128 v[186:189], v155 offset:3072
	ds_read_b128 v[190:193], v168 offset:32768
	ds_read_b128 v[194:197], v168 offset:33792
	ds_read_b128 v[198:201], v168 offset:34816
	ds_read_b128 v[202:205], v168 offset:35840
	ds_read_b128 v[206:209], v168 offset:36864
	ds_read_b128 v[210:213], v168 offset:37888
	ds_read_b128 v[214:217], v168 offset:38912
	ds_read_b128 v[218:221], v168 offset:39936
	s_mov_b32 m0, s26
	s_nop 0
	global_load_lds_dwordx4 v144, s[16:17]
	s_mov_b32 m0, s27
	s_nop 0
	global_load_lds_dwordx4 v140, s[16:17]
	s_add_u32 s16, s16, 0x4000
	s_addc_u32 s17, s17, 0
	s_mov_b32 m0, s28
	s_nop 0
	global_load_lds_dwordx4 v144, s[16:17]
	s_mov_b32 m0, s29
	s_nop 0
	global_load_lds_dwordx4 v140, s[16:17]
	s_waitcnt vmcnt(8)
	s_waitcnt lgkmcnt(0)
	s_barrier
	s_waitcnt lgkmcnt(0)
	v_mfma_f32_16x16x32_bf16 v[126:129], v[130:133], v[190:193], v[126:129]
	v_mfma_f32_16x16x32_bf16 v[122:125], v[158:161], v[190:193], v[122:125]
	v_mfma_f32_16x16x32_bf16 v[118:121], v[130:133], v[198:201], v[118:121]
	v_mfma_f32_16x16x32_bf16 v[114:117], v[158:161], v[198:201], v[114:117]
	v_mfma_f32_16x16x32_bf16 v[110:113], v[130:133], v[206:209], v[110:113]
	v_mfma_f32_16x16x32_bf16 v[106:109], v[158:161], v[206:209], v[106:109]
	v_mfma_f32_16x16x32_bf16 v[102:105], v[130:133], v[214:217], v[102:105]
	v_mfma_f32_16x16x32_bf16 v[98:101], v[158:161], v[214:217], v[98:101]
	v_mfma_f32_16x16x32_bf16 v[126:129], v[134:137], v[194:197], v[126:129]
	v_mfma_f32_16x16x32_bf16 v[122:125], v[170:173], v[194:197], v[122:125]
	v_mfma_f32_16x16x32_bf16 v[118:121], v[134:137], v[202:205], v[118:121]
	v_mfma_f32_16x16x32_bf16 v[114:117], v[170:173], v[202:205], v[114:117]
	v_mfma_f32_16x16x32_bf16 v[110:113], v[134:137], v[210:213], v[110:113]
	v_mfma_f32_16x16x32_bf16 v[106:109], v[170:173], v[210:213], v[106:109]
	v_mfma_f32_16x16x32_bf16 v[102:105], v[134:137], v[218:221], v[102:105]
	v_mfma_f32_16x16x32_bf16 v[98:101], v[170:173], v[218:221], v[98:101]
	v_mfma_f32_16x16x32_bf16 v[62:65], v[174:177], v[190:193], v[62:65]
	v_mfma_f32_16x16x32_bf16 v[58:61], v[182:185], v[190:193], v[58:61]
	v_mfma_f32_16x16x32_bf16 v[54:57], v[174:177], v[198:201], v[54:57]
	v_mfma_f32_16x16x32_bf16 v[50:53], v[182:185], v[198:201], v[50:53]
	v_mfma_f32_16x16x32_bf16 v[46:49], v[174:177], v[206:209], v[46:49]
	v_mfma_f32_16x16x32_bf16 v[42:45], v[182:185], v[206:209], v[42:45]
	v_mfma_f32_16x16x32_bf16 v[38:41], v[174:177], v[214:217], v[38:41]
	v_mfma_f32_16x16x32_bf16 v[34:37], v[182:185], v[214:217], v[34:37]
	v_mfma_f32_16x16x32_bf16 v[62:65], v[178:181], v[194:197], v[62:65]
	v_mfma_f32_16x16x32_bf16 v[58:61], v[186:189], v[194:197], v[58:61]
	v_mfma_f32_16x16x32_bf16 v[54:57], v[178:181], v[202:205], v[54:57]
	v_mfma_f32_16x16x32_bf16 v[50:53], v[186:189], v[202:205], v[50:53]
	v_mfma_f32_16x16x32_bf16 v[46:49], v[178:181], v[210:213], v[46:49]
	v_mfma_f32_16x16x32_bf16 v[42:45], v[186:189], v[210:213], v[42:45]
	v_mfma_f32_16x16x32_bf16 v[38:41], v[178:181], v[218:221], v[38:41]
	v_mfma_f32_16x16x32_bf16 v[34:37], v[186:189], v[218:221], v[34:37]
	s_barrier
	s_add_u32 s16, s14, 0x8000
	s_addc_u32 s17, s15, 0
	s_add_i32 s46, s46, s22
	s_mov_b32 m0, s46
	ds_read_b128 v[190:193], v168 offset:49152
	ds_read_b128 v[194:197], v168 offset:50176
	ds_read_b128 v[198:201], v168 offset:51200
	ds_read_b128 v[202:205], v168 offset:52224
	ds_read_b128 v[206:209], v168 offset:53248
	ds_read_b128 v[210:213], v168 offset:54272
	ds_read_b128 v[214:217], v168 offset:55296
	ds_read_b128 v[218:221], v168 offset:56320
	global_load_lds_dwordx4 v142, s[16:17]
	s_add_i32 m0, s46, 0x2000
	s_add_u32 s14, s14, 0xc000
	v_lshl_add_u64 v[162:163], s[16:17], 0, v[138:139]
	s_addc_u32 s15, s15, 0
	s_add_i32 s16, s47, s22
	global_load_lds_dwordx4 v[162:163], off
	s_mov_b32 m0, s16
	s_nop 0
	global_load_lds_dwordx4 v142, s[14:15]
	s_add_i32 m0, s16, 0x2000
	s_nop 0
	global_load_lds_dwordx4 v138, s[14:15]
	s_waitcnt vmcnt(6)
	s_waitcnt lgkmcnt(0)
	s_barrier
	s_waitcnt lgkmcnt(0)
	v_mfma_f32_16x16x32_bf16 v[94:97], v[130:133], v[190:193], v[94:97]
	v_mfma_f32_16x16x32_bf16 v[90:93], v[158:161], v[190:193], v[90:93]
	v_mfma_f32_16x16x32_bf16 v[86:89], v[130:133], v[198:201], v[86:89]
	v_mfma_f32_16x16x32_bf16 v[82:85], v[158:161], v[198:201], v[82:85]
	v_mfma_f32_16x16x32_bf16 v[78:81], v[130:133], v[206:209], v[78:81]
	v_mfma_f32_16x16x32_bf16 v[74:77], v[158:161], v[206:209], v[74:77]
	v_mfma_f32_16x16x32_bf16 v[70:73], v[130:133], v[214:217], v[70:73]
	v_mfma_f32_16x16x32_bf16 v[66:69], v[158:161], v[214:217], v[66:69]
	v_mfma_f32_16x16x32_bf16 v[94:97], v[134:137], v[194:197], v[94:97]
	v_mfma_f32_16x16x32_bf16 v[90:93], v[170:173], v[194:197], v[90:93]
	v_mfma_f32_16x16x32_bf16 v[86:89], v[134:137], v[202:205], v[86:89]
	v_mfma_f32_16x16x32_bf16 v[82:85], v[170:173], v[202:205], v[82:85]
	v_mfma_f32_16x16x32_bf16 v[78:81], v[134:137], v[210:213], v[78:81]
	v_mfma_f32_16x16x32_bf16 v[74:77], v[170:173], v[210:213], v[74:77]
	v_mfma_f32_16x16x32_bf16 v[70:73], v[134:137], v[218:221], v[70:73]
	v_mfma_f32_16x16x32_bf16 v[66:69], v[170:173], v[218:221], v[66:69]
	v_mfma_f32_16x16x32_bf16 v[30:33], v[174:177], v[190:193], v[30:33]
	v_mfma_f32_16x16x32_bf16 v[26:29], v[182:185], v[190:193], v[26:29]
	v_mfma_f32_16x16x32_bf16 v[22:25], v[174:177], v[198:201], v[22:25]
	v_mfma_f32_16x16x32_bf16 v[18:21], v[182:185], v[198:201], v[18:21]
	v_mfma_f32_16x16x32_bf16 v[14:17], v[174:177], v[206:209], v[14:17]
	v_mfma_f32_16x16x32_bf16 v[10:13], v[182:185], v[206:209], v[10:13]
	v_mfma_f32_16x16x32_bf16 v[6:9], v[174:177], v[214:217], v[6:9]
	v_mfma_f32_16x16x32_bf16 v[2:5], v[182:185], v[214:217], v[2:5]
	v_mfma_f32_16x16x32_bf16 v[30:33], v[178:181], v[194:197], v[30:33]
	v_mfma_f32_16x16x32_bf16 v[26:29], v[186:189], v[194:197], v[26:29]
	v_mfma_f32_16x16x32_bf16 v[22:25], v[178:181], v[202:205], v[22:25]
	v_mfma_f32_16x16x32_bf16 v[18:21], v[186:189], v[202:205], v[18:21]
	v_mfma_f32_16x16x32_bf16 v[14:17], v[178:181], v[210:213], v[14:17]
	v_mfma_f32_16x16x32_bf16 v[10:13], v[186:189], v[210:213], v[10:13]
	v_mfma_f32_16x16x32_bf16 v[6:9], v[178:181], v[218:221], v[6:9]
	v_mfma_f32_16x16x32_bf16 v[2:5], v[186:189], v[218:221], v[2:5]
	s_barrier
	s_add_i32 s45, s45, 2
	s_add_u32 s10, s10, 0x10000
	s_addc_u32 s11, s11, 0
	s_add_u32 s43, s43, 0x10000
	s_addc_u32 s44, s44, 0
	s_cmp_gt_u32 s45, 5
	s_cbranch_scc0 .LBB0_2685
	s_and_b64 vcc, exec, s[6:7]
	s_cbranch_vccz .LBB0_2688
	s_barrier

; #define PG8_STAGE(bufoff, gbase, voff) do { _Pragma("unroll") for (int _i = 0; _i < 2; ++_i) \
;         __builtin_amdgcn_global_load_lds((const unsigned*)((const char*)(gbase) + (voff)[_i]), (LAS unsigned*)(lds + (bufoff) + ldsw + _i * 8192), 16, 0, 0); } while (0)
; #define PG8_LDA(dst, b, h) do { _Pragma("unroll") for (int m = 0; m < 4; ++m) _Pragma("unroll") for (int k = 0; k < 2; ++k) dst[m][k] = *(const LAS bf16x8*)(lds + PG8_SA(b, h) + aoff + m * 2048 + k * 1024); } while (0)
; #define PG8_LDB(dst, b, h) do { _Pragma("unroll") for (int n = 0; n < 2; ++n) _Pragma("unroll") for (int k = 0; k < 2; ++k) dst[n][k] = *(const LAS bf16x8*)(lds + PG8_SB(b, h) + boff + n * 2048 + k * 1024); } while (0)
; #define PG8_WAIT_V(n) asm volatile("s_waitcnt vmcnt(" #n ")" ::: "memory")
; #define PG8_WAIT_L(n) asm volatile("s_waitcnt lgkmcnt(" #n ")" ::: "memory")
; #define PG8_BAR __builtin_amdgcn_s_barrier()
; #define PG8_SCHED __builtin_amdgcn_sched_barrier(0)
; template <class Epi, class Sched, bool I8 = false>
; __device__ __forceinline__ void gemm_phase(LAS unsigned char* lds, const Gemm g, const Sched& S, const Epi& E) {
;     ...
;             const char* a1 = cA + (size_t)(t + 1) * kstep;
;             const char* a2 = last ? nA : cA + (size_t)(t + 2) * kstep; const char* b2 = last ? nB : cB + (size_t)(t + 2) * kstep;
;             const char* a3 = a2 + kstep; const char* b3 = b2 + kstep;
;             PG8_LDB(B0, 0, 0); PG8_LDB(B1, 0, 1); PG8_SCHED; PG8_LDA(At, 0, 0); PG8_STAGE(PG8_SA(1, 1), a1 + hstepA, voffA);
;             PG8_WAIT_V(8); PG8_WAIT_L(0); PG8_BAR; PG8_MMA(0, 0, At, B0); PG8_MMA(0, 1, At, B1); PG8_BAR; PG8_SCHED;
;             PG8_LDA(At, 0, 1); PG8_STAGE(PG8_SB(0, 0), b2, voffB); PG8_STAGE(PG8_SB(0, 1), b2 + hstepB, voffB); PG8_STAGE(PG8_SA(0, 0), a2, voffA);
;             PG8_WAIT_V(8); PG8_WAIT_L(0); PG8_BAR; PG8_MMA(1, 0, At, B0); PG8_MMA(1, 1, At, B1); PG8_BAR; PG8_SCHED;
.LBB0_3744:
	ds_read_b128 v[130:133], v231
	ds_read_b128 v[134:137], v231 offset:1024
	ds_read_b128 v[138:141], v231 offset:2048
	ds_read_b128 v[142:145], v231 offset:3072
	ds_read_b128 v[146:149], v232
	ds_read_b128 v[150:153], v232 offset:1024
	ds_read_b128 v[154:157], v232 offset:2048
	ds_read_b128 v[158:161], v232 offset:3072
	s_add_u32 s34, s30, 0x4000
	s_addc_u32 s35, s31, 0
	s_cmp_eq_u32 s59, 60
	s_cselect_b32 s38, s23, s34
	s_cselect_b32 s39, s5, s35
	s_cselect_b32 s36, s29, s57
	s_cselect_b32 s37, s21, s58
	s_add_u32 s34, s38, 0x8000
	s_addc_u32 s35, s39, 0
	s_sub_u32 s98, s30, 0x4000
	s_subb_u32 s99, s31, 0
	ds_read_b128 v[162:165], v233
	ds_read_b128 v[166:169], v233 offset:1024
	ds_read_b128 v[170:173], v233 offset:2048
	ds_read_b128 v[174:177], v233 offset:3072
	ds_read_b128 v[178:181], v233 offset:4096
	ds_read_b128 v[182:185], v233 offset:5120
	ds_read_b128 v[186:189], v233 offset:6144
	ds_read_b128 v[190:193], v233 offset:7168
	s_mov_b32 m0, s51
	s_nop 0
	global_load_lds_dwordx4 v194, s[98:99]
	s_mov_b32 m0, s52
	s_nop 0
	global_load_lds_dwordx4 v198, s[98:99]
	s_add_i32 m0, s44, 0xc000
	s_nop 0
	global_load_lds_dwordx4 v204, s[30:31]
	s_add_i32 m0, s44, 0xe000
	s_nop 0
	global_load_lds_dwordx4 v206, s[30:31]
	s_waitcnt vmcnt(8)
	s_waitcnt lgkmcnt(0)
	s_barrier
	s_waitcnt lgkmcnt(0)
	v_mfma_f32_16x16x32_bf16 v[126:129], v[130:133], v[162:165], v[126:129]
	v_mfma_f32_16x16x32_bf16 v[122:125], v[138:141], v[162:165], v[122:125]
	v_mfma_f32_16x16x32_bf16 v[118:121], v[130:133], v[170:173], v[118:121]
	v_mfma_f32_16x16x32_bf16 v[110:113], v[138:141], v[170:173], v[110:113]
	v_mfma_f32_16x16x32_bf16 v[102:105], v[130:133], v[178:181], v[102:105]
	v_mfma_f32_16x16x32_bf16 v[94:97], v[138:141], v[178:181], v[94:97]
	v_mfma_f32_16x16x32_bf16 v[86:89], v[130:133], v[186:189], v[86:89]
	v_mfma_f32_16x16x32_bf16 v[78:81], v[138:141], v[186:189], v[78:81]
	v_mfma_f32_16x16x32_bf16 v[126:129], v[134:137], v[166:169], v[126:129]
	v_mfma_f32_16x16x32_bf16 v[122:125], v[142:145], v[166:169], v[122:125]
	v_mfma_f32_16x16x32_bf16 v[118:121], v[134:137], v[174:177], v[118:121]
	v_mfma_f32_16x16x32_bf16 v[110:113], v[142:145], v[174:177], v[110:113]
	v_mfma_f32_16x16x32_bf16 v[102:105], v[134:137], v[182:185], v[102:105]
	v_mfma_f32_16x16x32_bf16 v[94:97], v[142:145], v[182:185], v[94:97]
	v_mfma_f32_16x16x32_bf16 v[86:89], v[134:137], v[190:193], v[86:89]
	v_mfma_f32_16x16x32_bf16 v[78:81], v[142:145], v[190:193], v[78:81]
	v_mfma_f32_16x16x32_bf16 v[114:117], v[146:149], v[162:165], v[114:117]
	v_mfma_f32_16x16x32_bf16 v[106:109], v[154:157], v[162:165], v[106:109]
	v_mfma_f32_16x16x32_bf16 v[98:101], v[146:149], v[170:173], v[98:101]
	v_mfma_f32_16x16x32_bf16 v[90:93], v[154:157], v[170:173], v[90:93]
	v_mfma_f32_16x16x32_bf16 v[82:85], v[146:149], v[178:181], v[82:85]
	v_mfma_f32_16x16x32_bf16 v[74:77], v[154:157], v[178:181], v[74:77]
	v_mfma_f32_16x16x32_bf16 v[70:73], v[146:149], v[186:189], v[70:73]
	v_mfma_f32_16x16x32_bf16 v[66:69], v[154:157], v[186:189], v[66:69]
	v_mfma_f32_16x16x32_bf16 v[114:117], v[150:153], v[166:169], v[114:117]
	v_mfma_f32_16x16x32_bf16 v[106:109], v[158:161], v[166:169], v[106:109]
	v_mfma_f32_16x16x32_bf16 v[98:101], v[150:153], v[174:177], v[98:101]
	v_mfma_f32_16x16x32_bf16 v[90:93], v[158:161], v[174:177], v[90:93]
	v_mfma_f32_16x16x32_bf16 v[82:85], v[150:153], v[182:185], v[82:85]
	v_mfma_f32_16x16x32_bf16 v[74:77], v[158:161], v[182:185], v[74:77]
	v_mfma_f32_16x16x32_bf16 v[70:73], v[150:153], v[190:193], v[70:73]
	v_mfma_f32_16x16x32_bf16 v[66:69], v[158:161], v[190:193], v[66:69]
	s_barrier
	s_add_i32 s60, s55, s43
	s_mov_b32 m0, s60
	ds_read_b128 v[162:165], v233 offset:16384
	ds_read_b128 v[166:169], v233 offset:17408
	ds_read_b128 v[170:173], v233 offset:18432
	ds_read_b128 v[174:177], v233 offset:19456
	ds_read_b128 v[178:181], v233 offset:20480
	ds_read_b128 v[182:185], v233 offset:21504
	ds_read_b128 v[186:189], v233 offset:22528
	ds_read_b128 v[190:193], v233 offset:23552
	global_load_lds_dwordx4 v196, s[36:37]
	s_add_i32 m0, s60, 0x2000
	s_add_u32 s60, s36, 0x4000
	s_addc_u32 s61, s37, 0
	s_add_i32 s62, s56, s43
	global_load_lds_dwordx4 v200, s[36:37]
	s_mov_b32 m0, s62
	s_nop 0
	global_load_lds_dwordx4 v196, s[60:61]
	s_add_i32 m0, s62, 0x2000
	s_nop 0
	global_load_lds_dwordx4 v200, s[60:61]
	s_waitcnt vmcnt(6)
	s_waitcnt lgkmcnt(0)
	s_barrier
	s_waitcnt lgkmcnt(0)
	v_mfma_f32_16x16x32_bf16 v[62:65], v[130:133], v[162:165], v[62:65]
	v_mfma_f32_16x16x32_bf16 v[58:61], v[138:141], v[162:165], v[58:61]
	v_mfma_f32_16x16x32_bf16 v[54:57], v[130:133], v[170:173], v[54:57]
	v_mfma_f32_16x16x32_bf16 v[46:49], v[138:141], v[170:173], v[46:49]
	v_mfma_f32_16x16x32_bf16 v[38:41], v[130:133], v[178:181], v[38:41]
	v_mfma_f32_16x16x32_bf16 v[30:33], v[138:141], v[178:181], v[30:33]
	v_mfma_f32_16x16x32_bf16 v[22:25], v[130:133], v[186:189], v[22:25]
	v_mfma_f32_16x16x32_bf16 v[14:17], v[138:141], v[186:189], v[14:17]
	v_mfma_f32_16x16x32_bf16 v[62:65], v[134:137], v[166:169], v[62:65]
	v_mfma_f32_16x16x32_bf16 v[58:61], v[142:145], v[166:169], v[58:61]
	v_mfma_f32_16x16x32_bf16 v[54:57], v[134:137], v[174:177], v[54:57]
	v_mfma_f32_16x16x32_bf16 v[46:49], v[142:145], v[174:177], v[46:49]
	v_mfma_f32_16x16x32_bf16 v[38:41], v[134:137], v[182:185], v[38:41]
	v_mfma_f32_16x16x32_bf16 v[30:33], v[142:145], v[182:185], v[30:33]
	v_mfma_f32_16x16x32_bf16 v[22:25], v[134:137], v[190:193], v[22:25]
	v_mfma_f32_16x16x32_bf16 v[14:17], v[142:145], v[190:193], v[14:17]
	v_mfma_f32_16x16x32_bf16 v[50:53], v[146:149], v[162:165], v[50:53]
	v_mfma_f32_16x16x32_bf16 v[42:45], v[154:157], v[162:165], v[42:45]
	v_mfma_f32_16x16x32_bf16 v[34:37], v[146:149], v[170:173], v[34:37]
	v_mfma_f32_16x16x32_bf16 v[26:29], v[154:157], v[170:173], v[26:29]
	v_mfma_f32_16x16x32_bf16 v[18:21], v[146:149], v[178:181], v[18:21]
	v_mfma_f32_16x16x32_bf16 v[10:13], v[154:157], v[178:181], v[10:13]
	v_mfma_f32_16x16x32_bf16 v[6:9], v[146:149], v[186:189], v[6:9]
	v_mfma_f32_16x16x32_bf16 v[2:5], v[154:157], v[186:189], v[2:5]
	v_mfma_f32_16x16x32_bf16 v[50:53], v[150:153], v[166:169], v[50:53]
	v_mfma_f32_16x16x32_bf16 v[42:45], v[158:161], v[166:169], v[42:45]
	v_mfma_f32_16x16x32_bf16 v[34:37], v[150:153], v[174:177], v[34:37]
	v_mfma_f32_16x16x32_bf16 v[26:29], v[158:161], v[174:177], v[26:29]
	v_mfma_f32_16x16x32_bf16 v[18:21], v[150:153], v[182:185], v[18:21]
	v_mfma_f32_16x16x32_bf16 v[10:13], v[158:161], v[182:185], v[10:13]
	v_mfma_f32_16x16x32_bf16 v[6:9], v[150:153], v[190:193], v[6:9]
	v_mfma_f32_16x16x32_bf16 v[2:5], v[158:161], v[190:193], v[2:5]
	s_barrier
; #define PG8_STAGE(bufoff, gbase, voff) do { _Pragma("unroll") for (int _i = 0; _i < 2; ++_i) \
;         __builtin_amdgcn_global_load_lds((const unsigned*)((const char*)(gbase) + (voff)[_i]), (LAS unsigned*)(lds + (bufoff) + ldsw + _i * 8192), 16, 0, 0); } while (0)
; #define PG8_LDA(dst, b, h) do { _Pragma("unroll") for (int m = 0; m < 4; ++m) _Pragma("unroll") for (int k = 0; k < 2; ++k) dst[m][k] = *(const LAS bf16x8*)(lds + PG8_SA(b, h) + aoff + m * 2048 + k * 1024); } while (0)
; #define PG8_LDB(dst, b, h) do { _Pragma("unroll") for (int n = 0; n < 2; ++n) _Pragma("unroll") for (int k = 0; k < 2; ++k) dst[n][k] = *(const LAS bf16x8*)(lds + PG8_SB(b, h) + boff + n * 2048 + k * 1024); } while (0)
; #define PG8_WAIT_V(n) asm volatile("s_waitcnt vmcnt(" #n ")" ::: "memory")
; #define PG8_WAIT_L(n) asm volatile("s_waitcnt lgkmcnt(" #n ")" ::: "memory")
; #define PG8_BAR __builtin_amdgcn_s_barrier()
; #define PG8_SCHED __builtin_amdgcn_sched_barrier(0)
; template <class Epi, class Sched, bool I8 = false>
; __device__ __forceinline__ void gemm_phase(LAS unsigned char* lds, const Gemm g, const Sched& S, const Epi& E) {
;     ...
;             PG8_LDB(B0, 1, 0); PG8_LDB(B1, 1, 1); PG8_SCHED; PG8_LDA(At, 1, 0); PG8_STAGE(PG8_SA(0, 1), a2 + hstepA, voffA);
;             PG8_WAIT_V(8); PG8_WAIT_L(0); PG8_BAR; PG8_MMA(0, 0, At, B0); PG8_MMA(0, 1, At, B1); PG8_BAR; PG8_SCHED;
;             PG8_LDA(At, 1, 1); PG8_STAGE(PG8_SB(1, 0), b3, voffB); PG8_STAGE(PG8_SB(1, 1), b3 + hstepB, voffB); PG8_STAGE(PG8_SA(1, 0), a3, voffA);
;             PG8_WAIT_V(8); PG8_WAIT_L(0); PG8_BAR; PG8_MMA(1, 0, At, B0); PG8_MMA(1, 1, At, B1); PG8_BAR; PG8_SCHED;
;         }
	s_add_i32 s60, 0, 0x18000
	s_add_i32 s61, 0, 0x1c000
	v_add_u32_e32 v142, s60, v230
	v_add_u32_e32 v158, s61, v230
	ds_read_b128 v[130:133], v142
	ds_read_b128 v[134:137], v142 offset:1024
	ds_read_b128 v[138:141], v142 offset:2048
	ds_read_b128 v[142:145], v142 offset:3072
	ds_read_b128 v[146:149], v158
	ds_read_b128 v[150:153], v158 offset:1024
	ds_read_b128 v[154:157], v158 offset:2048
	ds_read_b128 v[158:161], v158 offset:3072
	ds_read_b128 v[162:165], v233 offset:32768
	ds_read_b128 v[166:169], v233 offset:33792
	ds_read_b128 v[170:173], v233 offset:34816
	ds_read_b128 v[174:177], v233 offset:35840
	ds_read_b128 v[178:181], v233 offset:36864
	ds_read_b128 v[182:185], v233 offset:37888
	ds_read_b128 v[186:189], v233 offset:38912
	ds_read_b128 v[190:193], v233 offset:39936
	s_mov_b32 m0, s44
	s_nop 0
	global_load_lds_dwordx4 v194, s[38:39]
	s_mov_b32 m0, s45
	s_nop 0
	global_load_lds_dwordx4 v198, s[38:39]
	s_add_u32 s38, s38, 0x4000
	s_addc_u32 s39, s39, 0
	s_mov_b32 m0, s46
	s_nop 0
	global_load_lds_dwordx4 v194, s[38:39]
	s_mov_b32 m0, s47
	s_nop 0
	global_load_lds_dwordx4 v198, s[38:39]
	s_waitcnt vmcnt(8)
	s_waitcnt lgkmcnt(0)
	s_barrier
	s_waitcnt lgkmcnt(0)
	v_mfma_f32_16x16x32_bf16 v[126:129], v[130:133], v[162:165], v[126:129]
	v_mfma_f32_16x16x32_bf16 v[122:125], v[138:141], v[162:165], v[122:125]
	v_mfma_f32_16x16x32_bf16 v[118:121], v[130:133], v[170:173], v[118:121]
	v_mfma_f32_16x16x32_bf16 v[110:113], v[138:141], v[170:173], v[110:113]
	v_mfma_f32_16x16x32_bf16 v[102:105], v[130:133], v[178:181], v[102:105]
	v_mfma_f32_16x16x32_bf16 v[94:97], v[138:141], v[178:181], v[94:97]
	v_mfma_f32_16x16x32_bf16 v[86:89], v[130:133], v[186:189], v[86:89]
	v_mfma_f32_16x16x32_bf16 v[78:81], v[138:141], v[186:189], v[78:81]
	v_mfma_f32_16x16x32_bf16 v[126:129], v[134:137], v[166:169], v[126:129]
	v_mfma_f32_16x16x32_bf16 v[122:125], v[142:145], v[166:169], v[122:125]
	v_mfma_f32_16x16x32_bf16 v[118:121], v[134:137], v[174:177], v[118:121]
	v_mfma_f32_16x16x32_bf16 v[110:113], v[142:145], v[174:177], v[110:113]
	v_mfma_f32_16x16x32_bf16 v[102:105], v[134:137], v[182:185], v[102:105]
	v_mfma_f32_16x16x32_bf16 v[94:97], v[142:145], v[182:185], v[94:97]
	v_mfma_f32_16x16x32_bf16 v[86:89], v[134:137], v[190:193], v[86:89]
	v_mfma_f32_16x16x32_bf16 v[78:81], v[142:145], v[190:193], v[78:81]
	v_mfma_f32_16x16x32_bf16 v[114:117], v[146:149], v[162:165], v[114:117]
	v_mfma_f32_16x16x32_bf16 v[106:109], v[154:157], v[162:165], v[106:109]
	v_mfma_f32_16x16x32_bf16 v[98:101], v[146:149], v[170:173], v[98:101]
	v_mfma_f32_16x16x32_bf16 v[90:93], v[154:157], v[170:173], v[90:93]
	v_mfma_f32_16x16x32_bf16 v[82:85], v[146:149], v[178:181], v[82:85]
	v_mfma_f32_16x16x32_bf16 v[74:77], v[154:157], v[178:181], v[74:77]
	v_mfma_f32_16x16x32_bf16 v[70:73], v[146:149], v[186:189], v[70:73]
	v_mfma_f32_16x16x32_bf16 v[66:69], v[154:157], v[186:189], v[66:69]
	v_mfma_f32_16x16x32_bf16 v[114:117], v[150:153], v[166:169], v[114:117]
	v_mfma_f32_16x16x32_bf16 v[106:109], v[158:161], v[166:169], v[106:109]
	v_mfma_f32_16x16x32_bf16 v[98:101], v[150:153], v[174:177], v[98:101]
	v_mfma_f32_16x16x32_bf16 v[90:93], v[158:161], v[174:177], v[90:93]
	v_mfma_f32_16x16x32_bf16 v[82:85], v[150:153], v[182:185], v[82:85]
	v_mfma_f32_16x16x32_bf16 v[74:77], v[158:161], v[182:185], v[74:77]
	v_mfma_f32_16x16x32_bf16 v[70:73], v[150:153], v[190:193], v[70:73]
	v_mfma_f32_16x16x32_bf16 v[66:69], v[158:161], v[190:193], v[66:69]
	s_barrier
	s_add_u32 s38, s36, 0x8000
	s_addc_u32 s39, s37, 0
	s_add_i32 s60, s60, s43
	s_mov_b32 m0, s60
	ds_read_b128 v[162:165], v233 offset:49152
	ds_read_b128 v[166:169], v233 offset:50176
	ds_read_b128 v[170:173], v233 offset:51200
	ds_read_b128 v[174:177], v233 offset:52224
	ds_read_b128 v[178:181], v233 offset:53248
	ds_read_b128 v[182:185], v233 offset:54272
	ds_read_b128 v[186:189], v233 offset:55296
	ds_read_b128 v[190:193], v233 offset:56320
	global_load_lds_dwordx4 v196, s[38:39]
	s_add_i32 m0, s60, 0x2000
	s_add_u32 s36, s36, 0xc000
	v_lshl_add_u64 v[212:213], s[38:39], 0, v[200:201]
	s_addc_u32 s37, s37, 0
	s_add_i32 s38, s61, s43
	global_load_lds_dwordx4 v[212:213], off
	s_mov_b32 m0, s38
	s_nop 0
	global_load_lds_dwordx4 v196, s[36:37]
	s_add_i32 m0, s38, 0x2000
	s_nop 0
	global_load_lds_dwordx4 v200, s[36:37]
	s_waitcnt vmcnt(6)
	s_waitcnt lgkmcnt(0)
	s_barrier
	s_waitcnt lgkmcnt(0)
	v_mfma_f32_16x16x32_bf16 v[62:65], v[130:133], v[162:165], v[62:65]
	v_mfma_f32_16x16x32_bf16 v[58:61], v[138:141], v[162:165], v[58:61]
	v_mfma_f32_16x16x32_bf16 v[54:57], v[130:133], v[170:173], v[54:57]
	v_mfma_f32_16x16x32_bf16 v[46:49], v[138:141], v[170:173], v[46:49]
	v_mfma_f32_16x16x32_bf16 v[38:41], v[130:133], v[178:181], v[38:41]
	v_mfma_f32_16x16x32_bf16 v[30:33], v[138:141], v[178:181], v[30:33]
	v_mfma_f32_16x16x32_bf16 v[22:25], v[130:133], v[186:189], v[22:25]
	v_mfma_f32_16x16x32_bf16 v[14:17], v[138:141], v[186:189], v[14:17]
	v_mfma_f32_16x16x32_bf16 v[62:65], v[134:137], v[166:169], v[62:65]
	v_mfma_f32_16x16x32_bf16 v[58:61], v[142:145], v[166:169], v[58:61]
	v_mfma_f32_16x16x32_bf16 v[54:57], v[134:137], v[174:177], v[54:57]
	v_mfma_f32_16x16x32_bf16 v[46:49], v[142:145], v[174:177], v[46:49]
	v_mfma_f32_16x16x32_bf16 v[38:41], v[134:137], v[182:185], v[38:41]
	v_mfma_f32_16x16x32_bf16 v[30:33], v[142:145], v[182:185], v[30:33]
	v_mfma_f32_16x16x32_bf16 v[22:25], v[134:137], v[190:193], v[22:25]
	v_mfma_f32_16x16x32_bf16 v[14:17], v[142:145], v[190:193], v[14:17]
	v_mfma_f32_16x16x32_bf16 v[50:53], v[146:149], v[162:165], v[50:53]
	v_mfma_f32_16x16x32_bf16 v[42:45], v[154:157], v[162:165], v[42:45]
	v_mfma_f32_16x16x32_bf16 v[34:37], v[146:149], v[170:173], v[34:37]
	v_mfma_f32_16x16x32_bf16 v[26:29], v[154:157], v[170:173], v[26:29]
	v_mfma_f32_16x16x32_bf16 v[18:21], v[146:149], v[178:181], v[18:21]
	v_mfma_f32_16x16x32_bf16 v[10:13], v[154:157], v[178:181], v[10:13]
	v_mfma_f32_16x16x32_bf16 v[6:9], v[146:149], v[186:189], v[6:9]
	v_mfma_f32_16x16x32_bf16 v[2:5], v[154:157], v[186:189], v[2:5]
	v_mfma_f32_16x16x32_bf16 v[50:53], v[150:153], v[166:169], v[50:53]
	v_mfma_f32_16x16x32_bf16 v[42:45], v[158:161], v[166:169], v[42:45]
	v_mfma_f32_16x16x32_bf16 v[34:37], v[150:153], v[174:177], v[34:37]
	v_mfma_f32_16x16x32_bf16 v[26:29], v[158:161], v[174:177], v[26:29]
	v_mfma_f32_16x16x32_bf16 v[18:21], v[150:153], v[182:185], v[18:21]
	v_mfma_f32_16x16x32_bf16 v[10:13], v[158:161], v[182:185], v[10:13]
	v_mfma_f32_16x16x32_bf16 v[6:9], v[150:153], v[190:193], v[6:9]
	v_mfma_f32_16x16x32_bf16 v[2:5], v[158:161], v[190:193], v[2:5]
	s_barrier
	s_add_i32 s59, s59, 2
	s_add_u32 s30, s30, 0x10000
	s_addc_u32 s31, s31, 0
	s_add_u32 s57, s57, 0x10000
	s_addc_u32 s58, s58, 0
	s_cmp_gt_u32 s59, 61
	s_cbranch_scc0 .LBB0_3744
	s_and_b64 vcc, exec, s[6:7]
	s_cbranch_vccz .LBB0_3747
	s_barrier

; #define PG8_STAGE(bufoff, gbase, voff) do { _Pragma("unroll") for (int _i = 0; _i < 2; ++_i) \
;         __builtin_amdgcn_global_load_lds((const unsigned*)((const char*)(gbase) + (voff)[_i]), (LAS unsigned*)(lds + (bufoff) + ldsw + _i * 8192), 16, 0, 0); } while (0)
; #define PG8_LDA(dst, b, h) do { _Pragma("unroll") for (int m = 0; m < 4; ++m) _Pragma("unroll") for (int k = 0; k < 2; ++k) dst[m][k] = *(const LAS bf16x8*)(lds + PG8_SA(b, h) + aoff + m * 2048 + k * 1024); } while (0)
; #define PG8_LDB(dst, b, h) do { _Pragma("unroll") for (int n = 0; n < 2; ++n) _Pragma("unroll") for (int k = 0; k < 2; ++k) dst[n][k] = *(const LAS bf16x8*)(lds + PG8_SB(b, h) + boff + n * 2048 + k * 1024); } while (0)
; #define PG8_WAIT_V(n) asm volatile("s_waitcnt vmcnt(" #n ")" ::: "memory")
; #define PG8_WAIT_L(n) asm volatile("s_waitcnt lgkmcnt(" #n ")" ::: "memory")
; #define PG8_BAR __builtin_amdgcn_s_barrier()
; #define PG8_SCHED __builtin_amdgcn_sched_barrier(0)
; template <class Epi, class Sched, bool I8 = false>
; __device__ __forceinline__ void gemm_phase(LAS unsigned char* lds, const Gemm g, const Sched& S, const Epi& E) {
;     ...
;             const char* a1 = cA + (size_t)(t + 1) * kstep;
;             const char* a2 = last ? nA : cA + (size_t)(t + 2) * kstep; const char* b2 = last ? nB : cB + (size_t)(t + 2) * kstep;
;             const char* a3 = a2 + kstep; const char* b3 = b2 + kstep;
;             PG8_LDB(B0, 0, 0); PG8_LDB(B1, 0, 1); PG8_SCHED; PG8_LDA(At, 0, 0); PG8_STAGE(PG8_SA(1, 1), a1 + hstepA, voffA);
;             PG8_WAIT_V(8); PG8_WAIT_L(0); PG8_BAR; PG8_MMA(0, 0, At, B0); PG8_MMA(0, 1, At, B1); PG8_BAR; PG8_SCHED;
;             PG8_LDA(At, 0, 1); PG8_STAGE(PG8_SB(0, 0), b2, voffB); PG8_STAGE(PG8_SB(0, 1), b2 + hstepB, voffB); PG8_STAGE(PG8_SA(0, 0), a2, voffA);
;             PG8_WAIT_V(8); PG8_WAIT_L(0); PG8_BAR; PG8_MMA(1, 0, At, B0); PG8_MMA(1, 1, At, B1); PG8_BAR; PG8_SCHED;
.LBB0_4168:
	ds_read_b128 v[66:69], v178
	ds_read_b128 v[70:73], v178 offset:1024
	ds_read_b128 v[74:77], v178 offset:2048
	ds_read_b128 v[78:81], v178 offset:3072
	ds_read_b128 v[146:149], v179
	ds_read_b128 v[150:153], v179 offset:1024
	ds_read_b128 v[172:175], v179 offset:2048
	ds_read_b128 v[182:185], v179 offset:3072
	s_add_u32 s22, s20, 0x4000
	s_addc_u32 s23, s21, 0
	s_cmpk_eq_i32 s51, 0x52
	s_cselect_b32 s26, s0, s22
	s_cselect_b32 s27, s1, s23
	s_cselect_b32 s24, s18, s49
	s_cselect_b32 s25, s19, s50
	s_add_u32 s22, s26, 0x8000
	s_addc_u32 s23, s27, 0
	s_sub_u32 s98, s20, 0x4000
	s_subb_u32 s99, s21, 0
	ds_read_b128 v[186:189], v180
	ds_read_b128 v[190:193], v180 offset:1024
	ds_read_b128 v[194:197], v180 offset:2048
	ds_read_b128 v[198:201], v180 offset:3072
	ds_read_b128 v[202:205], v180 offset:4096
	ds_read_b128 v[206:209], v180 offset:5120
	ds_read_b128 v[210:213], v180 offset:6144
	ds_read_b128 v[214:217], v180 offset:7168
	s_mov_b32 m0, s39
	s_nop 0
	global_load_lds_dwordx4 v154, s[98:99]
	s_mov_b32 m0, s40
	s_nop 0
	global_load_lds_dwordx4 v158, s[98:99]
	s_add_i32 m0, s34, 0xc000
	s_nop 0
	global_load_lds_dwordx4 v164, s[20:21]
	s_add_i32 m0, s34, 0xe000
	s_nop 0
	global_load_lds_dwordx4 v166, s[20:21]
	s_waitcnt vmcnt(8)
	s_waitcnt lgkmcnt(0)
	s_barrier
	s_waitcnt lgkmcnt(0)
	v_mfma_i32_16x16x64_i8 v[142:145], v[66:69], v[186:189], v[142:145]
	v_mfma_i32_16x16x64_i8 v[138:141], v[74:77], v[186:189], v[138:141]
	v_mfma_i32_16x16x64_i8 v[126:129], v[66:69], v[194:197], v[126:129]
	v_mfma_i32_16x16x64_i8 v[122:125], v[74:77], v[194:197], v[122:125]
	v_mfma_i32_16x16x64_i8 v[110:113], v[66:69], v[202:205], v[110:113]
	v_mfma_i32_16x16x64_i8 v[106:109], v[74:77], v[202:205], v[106:109]
	v_mfma_i32_16x16x64_i8 v[94:97], v[66:69], v[210:213], v[94:97]
	v_mfma_i32_16x16x64_i8 v[90:93], v[74:77], v[210:213], v[90:93]
	v_mfma_i32_16x16x64_i8 v[142:145], v[70:73], v[190:193], v[142:145]
	v_mfma_i32_16x16x64_i8 v[138:141], v[78:81], v[190:193], v[138:141]
	v_mfma_i32_16x16x64_i8 v[126:129], v[70:73], v[198:201], v[126:129]
	v_mfma_i32_16x16x64_i8 v[122:125], v[78:81], v[198:201], v[122:125]
	v_mfma_i32_16x16x64_i8 v[110:113], v[70:73], v[206:209], v[110:113]
	v_mfma_i32_16x16x64_i8 v[106:109], v[78:81], v[206:209], v[106:109]
	v_mfma_i32_16x16x64_i8 v[94:97], v[70:73], v[214:217], v[94:97]
	v_mfma_i32_16x16x64_i8 v[90:93], v[78:81], v[214:217], v[90:93]
	v_mfma_i32_16x16x64_i8 v[134:137], v[146:149], v[186:189], v[134:137]
	v_mfma_i32_16x16x64_i8 v[130:133], v[172:175], v[186:189], v[130:133]
	v_mfma_i32_16x16x64_i8 v[118:121], v[146:149], v[194:197], v[118:121]
	v_mfma_i32_16x16x64_i8 v[114:117], v[172:175], v[194:197], v[114:117]
	v_mfma_i32_16x16x64_i8 v[102:105], v[146:149], v[202:205], v[102:105]
	v_mfma_i32_16x16x64_i8 v[98:101], v[172:175], v[202:205], v[98:101]
	v_mfma_i32_16x16x64_i8 v[86:89], v[146:149], v[210:213], v[86:89]
	v_mfma_i32_16x16x64_i8 v[82:85], v[172:175], v[210:213], v[82:85]
	v_mfma_i32_16x16x64_i8 v[134:137], v[150:153], v[190:193], v[134:137]
	v_mfma_i32_16x16x64_i8 v[130:133], v[182:185], v[190:193], v[130:133]
	v_mfma_i32_16x16x64_i8 v[118:121], v[150:153], v[198:201], v[118:121]
	v_mfma_i32_16x16x64_i8 v[114:117], v[182:185], v[198:201], v[114:117]
	v_mfma_i32_16x16x64_i8 v[102:105], v[150:153], v[206:209], v[102:105]
	v_mfma_i32_16x16x64_i8 v[98:101], v[182:185], v[206:209], v[98:101]
	v_mfma_i32_16x16x64_i8 v[86:89], v[150:153], v[214:217], v[86:89]
	v_mfma_i32_16x16x64_i8 v[82:85], v[182:185], v[214:217], v[82:85]
	s_barrier
	s_add_i32 s52, s43, s33
	s_mov_b32 m0, s52
	ds_read_b128 v[186:189], v180 offset:16384
	ds_read_b128 v[190:193], v180 offset:17408
	ds_read_b128 v[194:197], v180 offset:18432
	ds_read_b128 v[198:201], v180 offset:19456
	ds_read_b128 v[202:205], v180 offset:20480
	ds_read_b128 v[206:209], v180 offset:21504
	ds_read_b128 v[210:213], v180 offset:22528
	ds_read_b128 v[214:217], v180 offset:23552
	global_load_lds_dwordx4 v156, s[24:25]
	s_add_i32 m0, s52, 0x2000
	s_add_u32 s52, s24, 0x4000
	s_addc_u32 s53, s25, 0
	s_add_i32 s54, s44, s33
	global_load_lds_dwordx4 v160, s[24:25]
	s_mov_b32 m0, s54
	s_nop 0
	global_load_lds_dwordx4 v156, s[52:53]
	s_add_i32 m0, s54, 0x2000
	s_nop 0
	global_load_lds_dwordx4 v160, s[52:53]
	s_waitcnt vmcnt(6)
	s_waitcnt lgkmcnt(0)
	s_barrier
	s_waitcnt lgkmcnt(0)
	v_mfma_i32_16x16x64_i8 v[62:65], v[66:69], v[186:189], v[62:65]
	v_mfma_i32_16x16x64_i8 v[58:61], v[74:77], v[186:189], v[58:61]
	v_mfma_i32_16x16x64_i8 v[46:49], v[66:69], v[194:197], v[46:49]
	v_mfma_i32_16x16x64_i8 v[42:45], v[74:77], v[194:197], v[42:45]
	v_mfma_i32_16x16x64_i8 v[30:33], v[66:69], v[202:205], v[30:33]
	v_mfma_i32_16x16x64_i8 v[26:29], v[74:77], v[202:205], v[26:29]
	v_mfma_i32_16x16x64_i8 v[14:17], v[66:69], v[210:213], v[14:17]
	v_mfma_i32_16x16x64_i8 v[10:13], v[74:77], v[210:213], v[10:13]
	v_mfma_i32_16x16x64_i8 v[62:65], v[70:73], v[190:193], v[62:65]
	v_mfma_i32_16x16x64_i8 v[58:61], v[78:81], v[190:193], v[58:61]
	v_mfma_i32_16x16x64_i8 v[46:49], v[70:73], v[198:201], v[46:49]
	v_mfma_i32_16x16x64_i8 v[42:45], v[78:81], v[198:201], v[42:45]
	v_mfma_i32_16x16x64_i8 v[30:33], v[70:73], v[206:209], v[30:33]
	v_mfma_i32_16x16x64_i8 v[26:29], v[78:81], v[206:209], v[26:29]
	v_mfma_i32_16x16x64_i8 v[14:17], v[70:73], v[214:217], v[14:17]
	v_mfma_i32_16x16x64_i8 v[10:13], v[78:81], v[214:217], v[10:13]
	v_mfma_i32_16x16x64_i8 v[54:57], v[146:149], v[186:189], v[54:57]
	v_mfma_i32_16x16x64_i8 v[50:53], v[172:175], v[186:189], v[50:53]
	v_mfma_i32_16x16x64_i8 v[38:41], v[146:149], v[194:197], v[38:41]
	v_mfma_i32_16x16x64_i8 v[34:37], v[172:175], v[194:197], v[34:37]
	v_mfma_i32_16x16x64_i8 v[22:25], v[146:149], v[202:205], v[22:25]
	v_mfma_i32_16x16x64_i8 v[18:21], v[172:175], v[202:205], v[18:21]
	v_mfma_i32_16x16x64_i8 v[6:9], v[146:149], v[210:213], v[6:9]
	v_mfma_i32_16x16x64_i8 v[2:5], v[172:175], v[210:213], v[2:5]
	v_mfma_i32_16x16x64_i8 v[54:57], v[150:153], v[190:193], v[54:57]
	v_mfma_i32_16x16x64_i8 v[50:53], v[182:185], v[190:193], v[50:53]
	v_mfma_i32_16x16x64_i8 v[38:41], v[150:153], v[198:201], v[38:41]
	v_mfma_i32_16x16x64_i8 v[34:37], v[182:185], v[198:201], v[34:37]
	v_mfma_i32_16x16x64_i8 v[22:25], v[150:153], v[206:209], v[22:25]
	v_mfma_i32_16x16x64_i8 v[18:21], v[182:185], v[206:209], v[18:21]
	v_mfma_i32_16x16x64_i8 v[6:9], v[150:153], v[214:217], v[6:9]
	v_mfma_i32_16x16x64_i8 v[2:5], v[182:185], v[214:217], v[2:5]
	s_barrier
; #define PG8_STAGE(bufoff, gbase, voff) do { _Pragma("unroll") for (int _i = 0; _i < 2; ++_i) \
;         __builtin_amdgcn_global_load_lds((const unsigned*)((const char*)(gbase) + (voff)[_i]), (LAS unsigned*)(lds + (bufoff) + ldsw + _i * 8192), 16, 0, 0); } while (0)
; #define PG8_LDA(dst, b, h) do { _Pragma("unroll") for (int m = 0; m < 4; ++m) _Pragma("unroll") for (int k = 0; k < 2; ++k) dst[m][k] = *(const LAS bf16x8*)(lds + PG8_SA(b, h) + aoff + m * 2048 + k * 1024); } while (0)
; #define PG8_LDB(dst, b, h) do { _Pragma("unroll") for (int n = 0; n < 2; ++n) _Pragma("unroll") for (int k = 0; k < 2; ++k) dst[n][k] = *(const LAS bf16x8*)(lds + PG8_SB(b, h) + boff + n * 2048 + k * 1024); } while (0)
; #define PG8_WAIT_V(n) asm volatile("s_waitcnt vmcnt(" #n ")" ::: "memory")
; #define PG8_WAIT_L(n) asm volatile("s_waitcnt lgkmcnt(" #n ")" ::: "memory")
; #define PG8_BAR __builtin_amdgcn_s_barrier()
; #define PG8_SCHED __builtin_amdgcn_sched_barrier(0)
; template <class Epi, class Sched, bool I8 = false>
; __device__ __forceinline__ void gemm_phase(LAS unsigned char* lds, const Gemm g, const Sched& S, const Epi& E) {
;     ...
;             PG8_LDB(B0, 1, 0); PG8_LDB(B1, 1, 1); PG8_SCHED; PG8_LDA(At, 1, 0); PG8_STAGE(PG8_SA(0, 1), a2 + hstepA, voffA);
;             PG8_WAIT_V(8); PG8_WAIT_L(0); PG8_BAR; PG8_MMA(0, 0, At, B0); PG8_MMA(0, 1, At, B1); PG8_BAR; PG8_SCHED;
;             PG8_LDA(At, 1, 1); PG8_STAGE(PG8_SB(1, 0), b3, voffB); PG8_STAGE(PG8_SB(1, 1), b3 + hstepB, voffB); PG8_STAGE(PG8_SA(1, 0), a3, voffA);
;             PG8_WAIT_V(8); PG8_WAIT_L(0); PG8_BAR; PG8_MMA(1, 0, At, B0); PG8_MMA(1, 1, At, B1); PG8_BAR; PG8_SCHED;
;         }
	s_add_i32 s52, 0, 0x18000
	s_add_i32 s53, 0, 0x1c000
	v_add_u32_e32 v78, s52, v176
	v_add_u32_e32 v162, s53, v176
	ds_read_b128 v[66:69], v78
	ds_read_b128 v[70:73], v78 offset:1024
	ds_read_b128 v[74:77], v78 offset:2048
	ds_read_b128 v[78:81], v78 offset:3072
	ds_read_b128 v[146:149], v162
	ds_read_b128 v[150:153], v162 offset:1024
	ds_read_b128 v[172:175], v162 offset:2048
	ds_read_b128 v[182:185], v162 offset:3072
	ds_read_b128 v[186:189], v180 offset:32768
	ds_read_b128 v[190:193], v180 offset:33792
	ds_read_b128 v[194:197], v180 offset:34816
	ds_read_b128 v[198:201], v180 offset:35840
	ds_read_b128 v[202:205], v180 offset:36864
	ds_read_b128 v[206:209], v180 offset:37888
	ds_read_b128 v[210:213], v180 offset:38912
	ds_read_b128 v[214:217], v180 offset:39936
	s_mov_b32 m0, s34
	s_nop 0
	global_load_lds_dwordx4 v154, s[26:27]
	s_mov_b32 m0, s35
	s_nop 0
	global_load_lds_dwordx4 v158, s[26:27]
	s_add_u32 s26, s26, 0x4000
	s_addc_u32 s27, s27, 0
	s_mov_b32 m0, s36
	s_nop 0
	global_load_lds_dwordx4 v154, s[26:27]
	s_mov_b32 m0, s37
	s_nop 0
	global_load_lds_dwordx4 v158, s[26:27]
	s_waitcnt vmcnt(8)
	s_waitcnt lgkmcnt(0)
	s_barrier
	s_waitcnt lgkmcnt(0)
	v_mfma_i32_16x16x64_i8 v[142:145], v[66:69], v[186:189], v[142:145]
	v_mfma_i32_16x16x64_i8 v[138:141], v[74:77], v[186:189], v[138:141]
	v_mfma_i32_16x16x64_i8 v[126:129], v[66:69], v[194:197], v[126:129]
	v_mfma_i32_16x16x64_i8 v[122:125], v[74:77], v[194:197], v[122:125]
	v_mfma_i32_16x16x64_i8 v[110:113], v[66:69], v[202:205], v[110:113]
	v_mfma_i32_16x16x64_i8 v[106:109], v[74:77], v[202:205], v[106:109]
	v_mfma_i32_16x16x64_i8 v[94:97], v[66:69], v[210:213], v[94:97]
	v_mfma_i32_16x16x64_i8 v[90:93], v[74:77], v[210:213], v[90:93]
	v_mfma_i32_16x16x64_i8 v[142:145], v[70:73], v[190:193], v[142:145]
	v_mfma_i32_16x16x64_i8 v[138:141], v[78:81], v[190:193], v[138:141]
	v_mfma_i32_16x16x64_i8 v[126:129], v[70:73], v[198:201], v[126:129]
	v_mfma_i32_16x16x64_i8 v[122:125], v[78:81], v[198:201], v[122:125]
	v_mfma_i32_16x16x64_i8 v[110:113], v[70:73], v[206:209], v[110:113]
	v_mfma_i32_16x16x64_i8 v[106:109], v[78:81], v[206:209], v[106:109]
	v_mfma_i32_16x16x64_i8 v[94:97], v[70:73], v[214:217], v[94:97]
	v_mfma_i32_16x16x64_i8 v[90:93], v[78:81], v[214:217], v[90:93]
	v_mfma_i32_16x16x64_i8 v[134:137], v[146:149], v[186:189], v[134:137]
	v_mfma_i32_16x16x64_i8 v[130:133], v[172:175], v[186:189], v[130:133]
	v_mfma_i32_16x16x64_i8 v[118:121], v[146:149], v[194:197], v[118:121]
	v_mfma_i32_16x16x64_i8 v[114:117], v[172:175], v[194:197], v[114:117]
	v_mfma_i32_16x16x64_i8 v[102:105], v[146:149], v[202:205], v[102:105]
	v_mfma_i32_16x16x64_i8 v[98:101], v[172:175], v[202:205], v[98:101]
	v_mfma_i32_16x16x64_i8 v[86:89], v[146:149], v[210:213], v[86:89]
	v_mfma_i32_16x16x64_i8 v[82:85], v[172:175], v[210:213], v[82:85]
	v_mfma_i32_16x16x64_i8 v[134:137], v[150:153], v[190:193], v[134:137]
	v_mfma_i32_16x16x64_i8 v[130:133], v[182:185], v[190:193], v[130:133]
	v_mfma_i32_16x16x64_i8 v[118:121], v[150:153], v[198:201], v[118:121]
	v_mfma_i32_16x16x64_i8 v[114:117], v[182:185], v[198:201], v[114:117]
	v_mfma_i32_16x16x64_i8 v[102:105], v[150:153], v[206:209], v[102:105]
	v_mfma_i32_16x16x64_i8 v[98:101], v[182:185], v[206:209], v[98:101]
	v_mfma_i32_16x16x64_i8 v[86:89], v[150:153], v[214:217], v[86:89]
	v_mfma_i32_16x16x64_i8 v[82:85], v[182:185], v[214:217], v[82:85]
	s_barrier
	s_add_u32 s26, s24, 0x8000
	s_addc_u32 s27, s25, 0
	s_add_i32 s52, s52, s33
	s_mov_b32 m0, s52
	ds_read_b128 v[186:189], v180 offset:49152
	ds_read_b128 v[190:193], v180 offset:50176
	ds_read_b128 v[194:197], v180 offset:51200
	ds_read_b128 v[198:201], v180 offset:52224
	ds_read_b128 v[202:205], v180 offset:53248
	ds_read_b128 v[206:209], v180 offset:54272
	ds_read_b128 v[210:213], v180 offset:55296
	ds_read_b128 v[214:217], v180 offset:56320
	global_load_lds_dwordx4 v156, s[26:27]
	s_add_i32 m0, s52, 0x2000
	s_add_u32 s24, s24, 0xc000
	v_lshl_add_u64 v[218:219], s[26:27], 0, v[160:161]
	s_addc_u32 s25, s25, 0
	s_add_i32 s26, s53, s33
	global_load_lds_dwordx4 v[218:219], off
	s_mov_b32 m0, s26
	s_nop 0
	global_load_lds_dwordx4 v156, s[24:25]
	s_add_i32 m0, s26, 0x2000
	s_nop 0
	global_load_lds_dwordx4 v160, s[24:25]
	s_waitcnt vmcnt(6)
	s_waitcnt lgkmcnt(0)
	s_barrier
	s_waitcnt lgkmcnt(0)
	v_mfma_i32_16x16x64_i8 v[62:65], v[66:69], v[186:189], v[62:65]
	v_mfma_i32_16x16x64_i8 v[58:61], v[74:77], v[186:189], v[58:61]
	v_mfma_i32_16x16x64_i8 v[46:49], v[66:69], v[194:197], v[46:49]
	v_mfma_i32_16x16x64_i8 v[42:45], v[74:77], v[194:197], v[42:45]
	v_mfma_i32_16x16x64_i8 v[30:33], v[66:69], v[202:205], v[30:33]
	v_mfma_i32_16x16x64_i8 v[26:29], v[74:77], v[202:205], v[26:29]
	v_mfma_i32_16x16x64_i8 v[14:17], v[66:69], v[210:213], v[14:17]
	v_mfma_i32_16x16x64_i8 v[10:13], v[74:77], v[210:213], v[10:13]
	v_mfma_i32_16x16x64_i8 v[62:65], v[70:73], v[190:193], v[62:65]
	v_mfma_i32_16x16x64_i8 v[58:61], v[78:81], v[190:193], v[58:61]
	v_mfma_i32_16x16x64_i8 v[46:49], v[70:73], v[198:201], v[46:49]
	v_mfma_i32_16x16x64_i8 v[42:45], v[78:81], v[198:201], v[42:45]
	v_mfma_i32_16x16x64_i8 v[30:33], v[70:73], v[206:209], v[30:33]
	v_mfma_i32_16x16x64_i8 v[26:29], v[78:81], v[206:209], v[26:29]
	v_mfma_i32_16x16x64_i8 v[14:17], v[70:73], v[214:217], v[14:17]
	v_mfma_i32_16x16x64_i8 v[10:13], v[78:81], v[214:217], v[10:13]
	v_mfma_i32_16x16x64_i8 v[54:57], v[146:149], v[186:189], v[54:57]
	v_mfma_i32_16x16x64_i8 v[50:53], v[172:175], v[186:189], v[50:53]
	v_mfma_i32_16x16x64_i8 v[38:41], v[146:149], v[194:197], v[38:41]
	v_mfma_i32_16x16x64_i8 v[34:37], v[172:175], v[194:197], v[34:37]
	v_mfma_i32_16x16x64_i8 v[22:25], v[146:149], v[202:205], v[22:25]
	v_mfma_i32_16x16x64_i8 v[18:21], v[172:175], v[202:205], v[18:21]
	v_mfma_i32_16x16x64_i8 v[6:9], v[146:149], v[210:213], v[6:9]
	v_mfma_i32_16x16x64_i8 v[2:5], v[172:175], v[210:213], v[2:5]
	v_mfma_i32_16x16x64_i8 v[54:57], v[150:153], v[190:193], v[54:57]
	v_mfma_i32_16x16x64_i8 v[50:53], v[182:185], v[190:193], v[50:53]
	v_mfma_i32_16x16x64_i8 v[38:41], v[150:153], v[198:201], v[38:41]
	v_mfma_i32_16x16x64_i8 v[34:37], v[182:185], v[198:201], v[34:37]
	v_mfma_i32_16x16x64_i8 v[22:25], v[150:153], v[206:209], v[22:25]
	v_mfma_i32_16x16x64_i8 v[18:21], v[182:185], v[206:209], v[18:21]
	v_mfma_i32_16x16x64_i8 v[6:9], v[150:153], v[214:217], v[6:9]
	v_mfma_i32_16x16x64_i8 v[2:5], v[182:185], v[214:217], v[2:5]
	s_barrier
	s_add_i32 s51, s51, 2
	s_add_u32 s20, s20, 0x10000
	s_addc_u32 s21, s21, 0
	s_add_u32 s49, s49, 0x10000
	s_addc_u32 s50, s50, 0
	s_cmpk_gt_u32 s51, 0x53
	s_cbranch_scc0 .LBB0_4168
	s_and_b64 vcc, exec, s[14:15]
	s_cbranch_vccz .LBB0_4171
	s_barrier
